# GEMM main loops: removed the back-to-back s_setprio 0/1 pair between the two MFMA groups of a phase
# speedup vs baseline: 1.0132x; 1.0132x over previous
; #define PG8_STAGE(bufoff, gbase, voff) do { _Pragma("unroll") for (int _i = 0; _i < 2; ++_i) \
;         __builtin_amdgcn_global_load_lds((const unsigned*)((const char*)(gbase) + (voff)[_i]), (LAS unsigned*)(lds + (bufoff) + ldsw + _i * 8192), 16, 0, 0); } while (0)
; #define PG8_LDA(dst, b, h) do { _Pragma("unroll") for (int m = 0; m < 4; ++m) _Pragma("unroll") for (int k = 0; k < 2; ++k) dst[m][k] = *(const LAS bf16x8*)(lds + PG8_SA(b, h) + aoff + m * 2048 + k * 1024); } while (0)
; #define PG8_LDB(dst, b, h) do { _Pragma("unroll") for (int n = 0; n < 2; ++n) _Pragma("unroll") for (int k = 0; k < 2; ++k) dst[n][k] = *(const LAS bf16x8*)(lds + PG8_SB(b, h) + boff + n * 2048 + k * 1024); } while (0)
; #define PG8_MMA(ai, bj, At, Bt) do { __builtin_amdgcn_s_setprio(1); _Pragma("unroll") for (int m = 0; m < 4; ++m) _Pragma("unroll") for (int n = 0; n < 2; ++n) _Pragma("unroll") for (int k = 0; k < 2; ++k) \
;         acc[ai][bj][m][n] = __builtin_amdgcn_mfma_f32_16x16x32_bf16(Bt[n][k], At[m][k], acc[ai][bj][m][n], 0, 0, 0); __builtin_amdgcn_s_setprio(0); } while (0)
; #define PG8_WAIT_V(n) asm volatile("s_waitcnt vmcnt(" #n ")" ::: "memory")
; #define PG8_WAIT_L(n) asm volatile("s_waitcnt lgkmcnt(" #n ")" ::: "memory")
; #define PG8_BAR __builtin_amdgcn_s_barrier()
; #define PG8_SCHED __builtin_amdgcn_sched_barrier(0)
; template <class Epi>
; __device__ __forceinline__ void gemm_phase(LAS unsigned char* lds, const Gemm g, const StaticOrder& S, const Epi& E) {
;     ...
;             PG8_LDB(B0, 0, 0); PG8_LDB(B1, 0, 1); PG8_SCHED; PG8_LDA(At, 0, 0); PG8_STAGE(PG8_SA(1, 1), a1 + hstepA, voffA);
;             PG8_WAIT_V(8); PG8_WAIT_L(0); PG8_BAR; PG8_MMA(0, 0, At, B0); PG8_MMA(0, 1, At, B1); PG8_BAR; PG8_SCHED;
;             PG8_LDA(At, 0, 1); PG8_STAGE(PG8_SB(0, 0), b2, voffB); PG8_STAGE(PG8_SB(0, 1), b2 + hstepB, voffB); PG8_STAGE(PG8_SA(0, 0), a2, voffA);
;             PG8_WAIT_V(8); PG8_WAIT_L(0); PG8_BAR; PG8_MMA(1, 0, At, B0); PG8_MMA(1, 1, At, B1); PG8_BAR; PG8_SCHED;
.LBB0_198:
	s_add_u32 s15, s22, 0xfff80080
	s_addc_u32 s16, s23, -1
	s_add_i32 s30, 0, 0x10000
	s_cmp_eq_u32 s14, 28
	s_cselect_b32 s63, s41, s16
	s_cselect_b32 s62, s40, s15
	v_add_u32_e32 v140, s30, v143
	s_cselect_b32 s55, s5, s11
	s_cselect_b32 s54, s6, s7
	s_add_i32 s15, 0, 0x14000
	ds_read_b128 v[146:149], v140
	ds_read_b128 v[150:153], v140 offset:1024
	ds_read_b128 v[154:157], v140 offset:2048
	ds_read_b128 v[158:161], v140 offset:3072
	v_add_u32_e32 v140, s15, v143
	ds_read_b128 v[162:165], v140
	ds_read_b128 v[166:169], v140 offset:1024
	ds_read_b128 v[170:173], v140 offset:2048
	ds_read_b128 v[174:177], v140 offset:3072
	v_lshl_add_u64 v[140:141], s[22:23], 0, v[138:139]
	s_add_i32 m0, s21, 0xc000
	ds_read_b128 v[178:181], v145
	ds_read_b128 v[182:185], v145 offset:1024
	ds_read_b128 v[186:189], v145 offset:2048
	ds_read_b128 v[190:193], v145 offset:3072
	ds_read_b128 v[194:197], v145 offset:4096
	ds_read_b128 v[202:205], v145 offset:5120
	ds_read_b128 v[206:209], v145 offset:6144
	ds_read_b128 v[210:213], v145 offset:7168
	global_load_lds_dwordx4 v[140:141], off
	v_lshl_add_u64 v[140:141], s[22:23], 0, v[136:137]
	s_add_i32 m0, s21, 0xe000
	s_nop 0
	global_load_lds_dwordx4 v[140:141], off
	s_waitcnt vmcnt(8)
	s_waitcnt lgkmcnt(0)
	s_barrier
	s_setprio 1
	s_waitcnt lgkmcnt(0)
	v_mfma_f32_16x16x32_bf16 v[126:129], v[146:149], v[178:181], v[126:129]
	v_mfma_f32_16x16x32_bf16 v[118:121], v[154:157], v[178:181], v[118:121]
	v_mfma_f32_16x16x32_bf16 v[110:113], v[146:149], v[186:189], v[110:113]
	v_mfma_f32_16x16x32_bf16 v[102:105], v[154:157], v[186:189], v[102:105]
	v_mfma_f32_16x16x32_bf16 v[94:97], v[146:149], v[194:197], v[94:97]
	v_mfma_f32_16x16x32_bf16 v[86:89], v[154:157], v[194:197], v[86:89]
	v_mfma_f32_16x16x32_bf16 v[78:81], v[146:149], v[206:209], v[78:81]
	v_mfma_f32_16x16x32_bf16 v[70:73], v[154:157], v[206:209], v[70:73]
	v_mfma_f32_16x16x32_bf16 v[126:129], v[150:153], v[182:185], v[126:129]
	v_mfma_f32_16x16x32_bf16 v[118:121], v[158:161], v[182:185], v[118:121]
	v_mfma_f32_16x16x32_bf16 v[110:113], v[150:153], v[190:193], v[110:113]
	v_mfma_f32_16x16x32_bf16 v[102:105], v[158:161], v[190:193], v[102:105]
	v_mfma_f32_16x16x32_bf16 v[94:97], v[150:153], v[202:205], v[94:97]
	v_mfma_f32_16x16x32_bf16 v[86:89], v[158:161], v[202:205], v[86:89]
	v_mfma_f32_16x16x32_bf16 v[78:81], v[150:153], v[210:213], v[78:81]
	v_mfma_f32_16x16x32_bf16 v[70:73], v[158:161], v[210:213], v[70:73]
	v_mfma_f32_16x16x32_bf16 v[122:125], v[162:165], v[178:181], v[122:125]
	v_mfma_f32_16x16x32_bf16 v[114:117], v[170:173], v[178:181], v[114:117]
	v_mfma_f32_16x16x32_bf16 v[106:109], v[162:165], v[186:189], v[106:109]
	v_mfma_f32_16x16x32_bf16 v[98:101], v[170:173], v[186:189], v[98:101]
	v_mfma_f32_16x16x32_bf16 v[90:93], v[162:165], v[194:197], v[90:93]
	v_mfma_f32_16x16x32_bf16 v[82:85], v[170:173], v[194:197], v[82:85]
	v_mfma_f32_16x16x32_bf16 v[74:77], v[162:165], v[206:209], v[74:77]
	v_mfma_f32_16x16x32_bf16 v[66:69], v[170:173], v[206:209], v[66:69]
	v_mfma_f32_16x16x32_bf16 v[122:125], v[166:169], v[182:185], v[122:125]
	v_mfma_f32_16x16x32_bf16 v[114:117], v[174:177], v[182:185], v[114:117]
	v_mfma_f32_16x16x32_bf16 v[106:109], v[166:169], v[190:193], v[106:109]
	v_mfma_f32_16x16x32_bf16 v[98:101], v[174:177], v[190:193], v[98:101]
	v_mfma_f32_16x16x32_bf16 v[90:93], v[166:169], v[202:205], v[90:93]
	v_mfma_f32_16x16x32_bf16 v[82:85], v[174:177], v[202:205], v[82:85]
	v_mfma_f32_16x16x32_bf16 v[74:77], v[166:169], v[210:213], v[74:77]
	v_mfma_f32_16x16x32_bf16 v[66:69], v[174:177], v[210:213], v[66:69]
	s_setprio 0
	s_barrier
	s_add_i32 s16, s30, s92
	v_lshl_add_u64 v[140:141], s[54:55], 0, v[0:1]
	s_mov_b32 m0, s16
	ds_read_b128 v[178:181], v145 offset:16384
	ds_read_b128 v[182:185], v145 offset:17408
	ds_read_b128 v[186:189], v145 offset:18432
	ds_read_b128 v[190:193], v145 offset:19456
	ds_read_b128 v[194:197], v145 offset:20480
	ds_read_b128 v[202:205], v145 offset:21504
	ds_read_b128 v[206:209], v145 offset:22528
	ds_read_b128 v[210:213], v145 offset:23552
	global_load_lds_dwordx4 v[140:141], off
	s_add_i32 m0, s16, 0x2000
	s_add_u32 s30, s54, 0x80000
	v_lshl_add_u64 v[198:199], s[54:55], 0, v[130:131]
	s_addc_u32 s31, s55, 0
	s_add_i32 s15, s15, s92
	global_load_lds_dwordx4 v[198:199], off
	v_lshl_add_u64 v[214:215], s[30:31], 0, v[0:1]
	s_mov_b32 m0, s15
	v_lshl_add_u64 v[228:229], s[62:63], 0, v[132:133]
	global_load_lds_dwordx4 v[214:215], off
	v_lshl_add_u64 v[214:215], s[30:31], 0, v[130:131]
	s_add_i32 m0, s15, 0x2000
	s_nop 0
	global_load_lds_dwordx4 v[214:215], off
	v_lshl_add_u64 v[214:215], s[62:63], 0, v[134:135]
	s_mov_b32 m0, s21
	s_nop 0
	global_load_lds_dwordx4 v[214:215], off
	s_mov_b32 m0, s96
	s_nop 0
	global_load_lds_dwordx4 v[228:229], off
	s_waitcnt vmcnt(8)
	s_waitcnt lgkmcnt(0)
	s_barrier
; #define PG8_STAGE(bufoff, gbase, voff) do { _Pragma("unroll") for (int _i = 0; _i < 2; ++_i) \
;         __builtin_amdgcn_global_load_lds((const unsigned*)((const char*)(gbase) + (voff)[_i]), (LAS unsigned*)(lds + (bufoff) + ldsw + _i * 8192), 16, 0, 0); } while (0)
; #define PG8_LDA(dst, b, h) do { _Pragma("unroll") for (int m = 0; m < 4; ++m) _Pragma("unroll") for (int k = 0; k < 2; ++k) dst[m][k] = *(const LAS bf16x8*)(lds + PG8_SA(b, h) + aoff + m * 2048 + k * 1024); } while (0)
; #define PG8_LDB(dst, b, h) do { _Pragma("unroll") for (int n = 0; n < 2; ++n) _Pragma("unroll") for (int k = 0; k < 2; ++k) dst[n][k] = *(const LAS bf16x8*)(lds + PG8_SB(b, h) + boff + n * 2048 + k * 1024); } while (0)
; #define PG8_MMA(ai, bj, At, Bt) do { __builtin_amdgcn_s_setprio(1); _Pragma("unroll") for (int m = 0; m < 4; ++m) _Pragma("unroll") for (int n = 0; n < 2; ++n) _Pragma("unroll") for (int k = 0; k < 2; ++k) \
;         acc[ai][bj][m][n] = __builtin_amdgcn_mfma_f32_16x16x32_bf16(Bt[n][k], At[m][k], acc[ai][bj][m][n], 0, 0, 0); __builtin_amdgcn_s_setprio(0); } while (0)
; #define PG8_WAIT_V(n) asm volatile("s_waitcnt vmcnt(" #n ")" ::: "memory")
; #define PG8_WAIT_L(n) asm volatile("s_waitcnt lgkmcnt(" #n ")" ::: "memory")
; #define PG8_BAR __builtin_amdgcn_s_barrier()
; #define PG8_SCHED __builtin_amdgcn_sched_barrier(0)
; template <class Epi>
; __device__ __forceinline__ void gemm_phase(LAS unsigned char* lds, const Gemm g, const StaticOrder& S, const Epi& E) {
;     ...
;             PG8_WAIT_V(8); PG8_WAIT_L(0); PG8_BAR; PG8_MMA(1, 0, At, B0); PG8_MMA(1, 1, At, B1); PG8_BAR; PG8_SCHED;
;             PG8_LDB(B0, 1, 0); PG8_LDB(B1, 1, 1); PG8_SCHED; PG8_LDA(At, 1, 0); PG8_STAGE(PG8_SA(0, 1), a2 + hstepA, voffA);
;             PG8_WAIT_V(8); PG8_WAIT_L(0); PG8_BAR; PG8_MMA(0, 0, At, B0); PG8_MMA(0, 1, At, B1); PG8_BAR; PG8_SCHED;
	s_setprio 1
	s_waitcnt lgkmcnt(0)
	v_mfma_f32_16x16x32_bf16 v[62:65], v[146:149], v[178:181], v[62:65]
	v_mfma_f32_16x16x32_bf16 v[54:57], v[154:157], v[178:181], v[54:57]
	v_mfma_f32_16x16x32_bf16 v[46:49], v[146:149], v[186:189], v[46:49]
	v_mfma_f32_16x16x32_bf16 v[38:41], v[154:157], v[186:189], v[38:41]
	v_mfma_f32_16x16x32_bf16 v[30:33], v[146:149], v[194:197], v[30:33]
	v_mfma_f32_16x16x32_bf16 v[22:25], v[154:157], v[194:197], v[22:25]
	v_mfma_f32_16x16x32_bf16 v[14:17], v[146:149], v[206:209], v[14:17]
	v_mfma_f32_16x16x32_bf16 v[6:9], v[154:157], v[206:209], v[6:9]
	v_mfma_f32_16x16x32_bf16 v[62:65], v[150:153], v[182:185], v[62:65]
	v_mfma_f32_16x16x32_bf16 v[54:57], v[158:161], v[182:185], v[54:57]
	v_mfma_f32_16x16x32_bf16 v[46:49], v[150:153], v[190:193], v[46:49]
	v_mfma_f32_16x16x32_bf16 v[38:41], v[158:161], v[190:193], v[38:41]
	v_mfma_f32_16x16x32_bf16 v[30:33], v[150:153], v[202:205], v[30:33]
	v_mfma_f32_16x16x32_bf16 v[22:25], v[158:161], v[202:205], v[22:25]
	v_mfma_f32_16x16x32_bf16 v[14:17], v[150:153], v[210:213], v[14:17]
	v_mfma_f32_16x16x32_bf16 v[6:9], v[158:161], v[210:213], v[6:9]
	v_mfma_f32_16x16x32_bf16 v[58:61], v[162:165], v[178:181], v[58:61]
	v_mfma_f32_16x16x32_bf16 v[50:53], v[170:173], v[178:181], v[50:53]
	v_mfma_f32_16x16x32_bf16 v[42:45], v[162:165], v[186:189], v[42:45]
	v_mfma_f32_16x16x32_bf16 v[34:37], v[170:173], v[186:189], v[34:37]
	v_mfma_f32_16x16x32_bf16 v[26:29], v[162:165], v[194:197], v[26:29]
	v_mfma_f32_16x16x32_bf16 v[18:21], v[170:173], v[194:197], v[18:21]
	v_mfma_f32_16x16x32_bf16 v[10:13], v[162:165], v[206:209], v[10:13]
	v_mfma_f32_16x16x32_bf16 v[2:5], v[170:173], v[206:209], v[2:5]
	v_mfma_f32_16x16x32_bf16 v[58:61], v[166:169], v[182:185], v[58:61]
	v_mfma_f32_16x16x32_bf16 v[50:53], v[174:177], v[182:185], v[50:53]
	v_mfma_f32_16x16x32_bf16 v[42:45], v[166:169], v[190:193], v[42:45]
	v_mfma_f32_16x16x32_bf16 v[34:37], v[174:177], v[190:193], v[34:37]
	v_mfma_f32_16x16x32_bf16 v[26:29], v[166:169], v[202:205], v[26:29]
	v_mfma_f32_16x16x32_bf16 v[18:21], v[174:177], v[202:205], v[18:21]
	v_mfma_f32_16x16x32_bf16 v[10:13], v[166:169], v[210:213], v[10:13]
	v_mfma_f32_16x16x32_bf16 v[2:5], v[174:177], v[210:213], v[2:5]
	s_setprio 0
	s_barrier
	s_add_i32 s15, 0, 0x18000
	s_add_i32 s16, 0, 0x1c000
	v_add_u32_e32 v158, s15, v143
	v_add_u32_e32 v174, s16, v143
	ds_read_b128 v[146:149], v158
	ds_read_b128 v[150:153], v158 offset:1024
	ds_read_b128 v[154:157], v158 offset:2048
	ds_read_b128 v[158:161], v158 offset:3072
	ds_read_b128 v[162:165], v174
	ds_read_b128 v[166:169], v174 offset:1024
	ds_read_b128 v[170:173], v174 offset:2048
	ds_read_b128 v[174:177], v174 offset:3072
	s_add_u32 s30, s62, 0x80000
	s_addc_u32 s31, s63, 0
	s_mov_b32 m0, s97
	v_lshl_add_u64 v[230:231], s[30:31], 0, v[134:135]
	ds_read_b128 v[178:181], v145 offset:32768
	ds_read_b128 v[182:185], v145 offset:33792
	ds_read_b128 v[186:189], v145 offset:34816
	ds_read_b128 v[190:193], v145 offset:35840
	ds_read_b128 v[194:197], v145 offset:36864
	ds_read_b128 v[202:205], v145 offset:37888
	ds_read_b128 v[206:209], v145 offset:38912
	ds_read_b128 v[210:213], v145 offset:39936
	global_load_lds_dwordx4 v[230:231], off
	v_lshl_add_u64 v[230:231], s[30:31], 0, v[132:133]
	s_mov_b32 m0, s68
	s_nop 0
	global_load_lds_dwordx4 v[230:231], off
	s_waitcnt vmcnt(8)
	s_waitcnt lgkmcnt(0)
	s_barrier
	s_setprio 1
	s_waitcnt lgkmcnt(0)
	v_mfma_f32_16x16x32_bf16 v[126:129], v[146:149], v[178:181], v[126:129]
	v_mfma_f32_16x16x32_bf16 v[118:121], v[154:157], v[178:181], v[118:121]
	v_mfma_f32_16x16x32_bf16 v[110:113], v[146:149], v[186:189], v[110:113]
	v_mfma_f32_16x16x32_bf16 v[102:105], v[154:157], v[186:189], v[102:105]
	v_mfma_f32_16x16x32_bf16 v[94:97], v[146:149], v[194:197], v[94:97]
	v_mfma_f32_16x16x32_bf16 v[86:89], v[154:157], v[194:197], v[86:89]
	v_mfma_f32_16x16x32_bf16 v[78:81], v[146:149], v[206:209], v[78:81]
	v_mfma_f32_16x16x32_bf16 v[70:73], v[154:157], v[206:209], v[70:73]
	v_mfma_f32_16x16x32_bf16 v[126:129], v[150:153], v[182:185], v[126:129]
	v_mfma_f32_16x16x32_bf16 v[118:121], v[158:161], v[182:185], v[118:121]
	v_mfma_f32_16x16x32_bf16 v[110:113], v[150:153], v[190:193], v[110:113]
	v_mfma_f32_16x16x32_bf16 v[102:105], v[158:161], v[190:193], v[102:105]
	v_mfma_f32_16x16x32_bf16 v[94:97], v[150:153], v[202:205], v[94:97]
	v_mfma_f32_16x16x32_bf16 v[86:89], v[158:161], v[202:205], v[86:89]
	v_mfma_f32_16x16x32_bf16 v[78:81], v[150:153], v[210:213], v[78:81]
	v_mfma_f32_16x16x32_bf16 v[70:73], v[158:161], v[210:213], v[70:73]
	v_mfma_f32_16x16x32_bf16 v[122:125], v[162:165], v[178:181], v[122:125]
	v_mfma_f32_16x16x32_bf16 v[114:117], v[170:173], v[178:181], v[114:117]
	v_mfma_f32_16x16x32_bf16 v[106:109], v[162:165], v[186:189], v[106:109]
	v_mfma_f32_16x16x32_bf16 v[98:101], v[170:173], v[186:189], v[98:101]
	v_mfma_f32_16x16x32_bf16 v[90:93], v[162:165], v[194:197], v[90:93]
	v_mfma_f32_16x16x32_bf16 v[82:85], v[170:173], v[194:197], v[82:85]
	v_mfma_f32_16x16x32_bf16 v[74:77], v[162:165], v[206:209], v[74:77]
	v_mfma_f32_16x16x32_bf16 v[66:69], v[170:173], v[206:209], v[66:69]
	v_mfma_f32_16x16x32_bf16 v[122:125], v[166:169], v[182:185], v[122:125]
	v_mfma_f32_16x16x32_bf16 v[114:117], v[174:177], v[182:185], v[114:117]
	v_mfma_f32_16x16x32_bf16 v[106:109], v[166:169], v[190:193], v[106:109]
	v_mfma_f32_16x16x32_bf16 v[98:101], v[174:177], v[190:193], v[98:101]
	v_mfma_f32_16x16x32_bf16 v[90:93], v[166:169], v[202:205], v[90:93]
	v_mfma_f32_16x16x32_bf16 v[82:85], v[174:177], v[202:205], v[82:85]
	v_mfma_f32_16x16x32_bf16 v[74:77], v[166:169], v[210:213], v[74:77]
	v_mfma_f32_16x16x32_bf16 v[66:69], v[174:177], v[210:213], v[66:69]
	s_setprio 0
	s_barrier
; #define PG8_STAGE(bufoff, gbase, voff) do { _Pragma("unroll") for (int _i = 0; _i < 2; ++_i) \
;         __builtin_amdgcn_global_load_lds((const unsigned*)((const char*)(gbase) + (voff)[_i]), (LAS unsigned*)(lds + (bufoff) + ldsw + _i * 8192), 16, 0, 0); } while (0)
; #define PG8_LDA(dst, b, h) do { _Pragma("unroll") for (int m = 0; m < 4; ++m) _Pragma("unroll") for (int k = 0; k < 2; ++k) dst[m][k] = *(const LAS bf16x8*)(lds + PG8_SA(b, h) + aoff + m * 2048 + k * 1024); } while (0)
; #define PG8_MMA(ai, bj, At, Bt) do { __builtin_amdgcn_s_setprio(1); _Pragma("unroll") for (int m = 0; m < 4; ++m) _Pragma("unroll") for (int n = 0; n < 2; ++n) _Pragma("unroll") for (int k = 0; k < 2; ++k) \
;         acc[ai][bj][m][n] = __builtin_amdgcn_mfma_f32_16x16x32_bf16(Bt[n][k], At[m][k], acc[ai][bj][m][n], 0, 0, 0); __builtin_amdgcn_s_setprio(0); } while (0)
; #define PG8_WAIT_V(n) asm volatile("s_waitcnt vmcnt(" #n ")" ::: "memory")
; #define PG8_WAIT_L(n) asm volatile("s_waitcnt lgkmcnt(" #n ")" ::: "memory")
; #define PG8_BAR __builtin_amdgcn_s_barrier()
; #define PG8_SCHED __builtin_amdgcn_sched_barrier(0)
; template <class Epi>
; __device__ __forceinline__ void gemm_phase(LAS unsigned char* lds, const Gemm g, const StaticOrder& S, const Epi& E) {
;     ...
;             PG8_LDA(At, 1, 1); PG8_STAGE(PG8_SB(1, 0), b3, voffB); PG8_STAGE(PG8_SB(1, 1), b3 + hstepB, voffB); PG8_STAGE(PG8_SA(1, 0), a3, voffA);
;             PG8_WAIT_V(8); PG8_WAIT_L(0); PG8_BAR; PG8_MMA(1, 0, At, B0); PG8_MMA(1, 1, At, B1); PG8_BAR; PG8_SCHED;
;         }
	s_add_i32 s15, s15, s92
	v_lshl_add_u64 v[140:141], v[140:141], 0, s[24:25]
	s_mov_b32 m0, s15
	ds_read_b128 v[178:181], v145 offset:49152
	ds_read_b128 v[182:185], v145 offset:50176
	ds_read_b128 v[186:189], v145 offset:51200
	ds_read_b128 v[190:193], v145 offset:52224
	ds_read_b128 v[194:197], v145 offset:53248
	ds_read_b128 v[202:205], v145 offset:54272
	ds_read_b128 v[206:209], v145 offset:55296
	ds_read_b128 v[210:213], v145 offset:56320
	global_load_lds_dwordx4 v[140:141], off
	s_add_i32 m0, s15, 0x2000
	s_add_u32 s30, s54, 0x80080
	v_lshl_add_u64 v[140:141], v[198:199], 0, s[24:25]
	s_addc_u32 s31, s55, 0
	s_add_i32 s15, s16, s92
	global_load_lds_dwordx4 v[140:141], off
	v_lshl_add_u64 v[140:141], s[30:31], 0, v[0:1]
	s_mov_b32 m0, s15
	s_nop 0
	global_load_lds_dwordx4 v[140:141], off
	v_lshl_add_u64 v[140:141], s[30:31], 0, v[130:131]
	s_add_i32 m0, s15, 0x2000
	s_nop 0
	global_load_lds_dwordx4 v[140:141], off
	v_lshl_add_u64 v[140:141], v[214:215], 0, s[24:25]
	s_mov_b32 m0, s69
	s_nop 0
	global_load_lds_dwordx4 v[140:141], off
	v_lshl_add_u64 v[140:141], v[228:229], 0, s[24:25]
	s_mov_b32 m0, s66
	s_nop 0
	global_load_lds_dwordx4 v[140:141], off
	s_waitcnt vmcnt(8)
	s_waitcnt lgkmcnt(0)
	s_barrier
	s_setprio 1
	s_waitcnt lgkmcnt(0)
	v_mfma_f32_16x16x32_bf16 v[62:65], v[146:149], v[178:181], v[62:65]
	v_mfma_f32_16x16x32_bf16 v[54:57], v[154:157], v[178:181], v[54:57]
	v_mfma_f32_16x16x32_bf16 v[46:49], v[146:149], v[186:189], v[46:49]
	v_mfma_f32_16x16x32_bf16 v[38:41], v[154:157], v[186:189], v[38:41]
	v_mfma_f32_16x16x32_bf16 v[30:33], v[146:149], v[194:197], v[30:33]
	v_mfma_f32_16x16x32_bf16 v[22:25], v[154:157], v[194:197], v[22:25]
	v_mfma_f32_16x16x32_bf16 v[14:17], v[146:149], v[206:209], v[14:17]
	v_mfma_f32_16x16x32_bf16 v[6:9], v[154:157], v[206:209], v[6:9]
	v_mfma_f32_16x16x32_bf16 v[62:65], v[150:153], v[182:185], v[62:65]
	v_mfma_f32_16x16x32_bf16 v[54:57], v[158:161], v[182:185], v[54:57]
	v_mfma_f32_16x16x32_bf16 v[46:49], v[150:153], v[190:193], v[46:49]
	v_mfma_f32_16x16x32_bf16 v[38:41], v[158:161], v[190:193], v[38:41]
	v_mfma_f32_16x16x32_bf16 v[30:33], v[150:153], v[202:205], v[30:33]
	v_mfma_f32_16x16x32_bf16 v[22:25], v[158:161], v[202:205], v[22:25]
	v_mfma_f32_16x16x32_bf16 v[14:17], v[150:153], v[210:213], v[14:17]
	v_mfma_f32_16x16x32_bf16 v[6:9], v[158:161], v[210:213], v[6:9]
	v_mfma_f32_16x16x32_bf16 v[58:61], v[162:165], v[178:181], v[58:61]
	v_mfma_f32_16x16x32_bf16 v[50:53], v[170:173], v[178:181], v[50:53]
	v_mfma_f32_16x16x32_bf16 v[42:45], v[162:165], v[186:189], v[42:45]
	v_mfma_f32_16x16x32_bf16 v[34:37], v[170:173], v[186:189], v[34:37]
	v_mfma_f32_16x16x32_bf16 v[26:29], v[162:165], v[194:197], v[26:29]
	v_mfma_f32_16x16x32_bf16 v[18:21], v[170:173], v[194:197], v[18:21]
	v_mfma_f32_16x16x32_bf16 v[10:13], v[162:165], v[206:209], v[10:13]
	v_mfma_f32_16x16x32_bf16 v[2:5], v[170:173], v[206:209], v[2:5]
	v_mfma_f32_16x16x32_bf16 v[58:61], v[166:169], v[182:185], v[58:61]
	v_mfma_f32_16x16x32_bf16 v[50:53], v[174:177], v[182:185], v[50:53]
	v_mfma_f32_16x16x32_bf16 v[42:45], v[166:169], v[190:193], v[42:45]
	v_mfma_f32_16x16x32_bf16 v[34:37], v[174:177], v[190:193], v[34:37]
	v_mfma_f32_16x16x32_bf16 v[26:29], v[166:169], v[202:205], v[26:29]
	v_mfma_f32_16x16x32_bf16 v[18:21], v[174:177], v[202:205], v[18:21]
	v_mfma_f32_16x16x32_bf16 v[10:13], v[166:169], v[210:213], v[10:13]
	v_mfma_f32_16x16x32_bf16 v[2:5], v[174:177], v[210:213], v[2:5]
	s_setprio 0
	s_barrier
	s_add_i32 s14, s14, 2
	s_add_u32 s7, s7, 0x100
	s_addc_u32 s11, s11, 0
	s_add_u32 s22, s22, 0x100
	s_addc_u32 s23, s23, 0
	s_cmp_gt_u32 s14, 29
	s_cbranch_scc0 .LBB0_198
	s_and_b64 vcc, exec, s[46:47]
	s_cbranch_vccz .LBB0_201
	s_barrier

; #define PG8_STAGE(bufoff, gbase, voff) do { _Pragma("unroll") for (int _i = 0; _i < 2; ++_i) \
;         __builtin_amdgcn_global_load_lds((const unsigned*)((const char*)(gbase) + (voff)[_i]), (LAS unsigned*)(lds + (bufoff) + ldsw + _i * 8192), 16, 0, 0); } while (0)
; #define PG8_LDA(dst, b, h) do { _Pragma("unroll") for (int m = 0; m < 4; ++m) _Pragma("unroll") for (int k = 0; k < 2; ++k) dst[m][k] = *(const LAS bf16x8*)(lds + PG8_SA(b, h) + aoff + m * 2048 + k * 1024); } while (0)
; #define PG8_LDB(dst, b, h) do { _Pragma("unroll") for (int n = 0; n < 2; ++n) _Pragma("unroll") for (int k = 0; k < 2; ++k) dst[n][k] = *(const LAS bf16x8*)(lds + PG8_SB(b, h) + boff + n * 2048 + k * 1024); } while (0)
; #define PG8_MMA(ai, bj, At, Bt) do { __builtin_amdgcn_s_setprio(1); _Pragma("unroll") for (int m = 0; m < 4; ++m) _Pragma("unroll") for (int n = 0; n < 2; ++n) _Pragma("unroll") for (int k = 0; k < 2; ++k) \
;         acc[ai][bj][m][n] = __builtin_amdgcn_mfma_f32_16x16x32_bf16(Bt[n][k], At[m][k], acc[ai][bj][m][n], 0, 0, 0); __builtin_amdgcn_s_setprio(0); } while (0)
; #define PG8_WAIT_V(n) asm volatile("s_waitcnt vmcnt(" #n ")" ::: "memory")
; #define PG8_WAIT_L(n) asm volatile("s_waitcnt lgkmcnt(" #n ")" ::: "memory")
; #define PG8_BAR __builtin_amdgcn_s_barrier()
; #define PG8_SCHED __builtin_amdgcn_sched_barrier(0)
; template <class Epi>
; __device__ __forceinline__ void gemm_phase(LAS unsigned char* lds, const Gemm g, const StaticOrder& S, const Epi& E) {
;     ...
;             PG8_LDB(B0, 0, 0); PG8_LDB(B1, 0, 1); PG8_SCHED; PG8_LDA(At, 0, 0); PG8_STAGE(PG8_SA(1, 1), a1 + hstepA, voffA);
;             PG8_WAIT_V(8); PG8_WAIT_L(0); PG8_BAR; PG8_MMA(0, 0, At, B0); PG8_MMA(0, 1, At, B1); PG8_BAR; PG8_SCHED;
;             PG8_LDA(At, 0, 1); PG8_STAGE(PG8_SB(0, 0), b2, voffB); PG8_STAGE(PG8_SB(0, 1), b2 + hstepB, voffB); PG8_STAGE(PG8_SA(0, 0), a2, voffA);
;             PG8_WAIT_V(8); PG8_WAIT_L(0); PG8_BAR; PG8_MMA(1, 0, At, B0); PG8_MMA(1, 1, At, B1); PG8_BAR; PG8_SCHED;
.LBB0_227:
	s_add_i32 s58, s57, 2
	s_add_u32 s30, s54, 0x80
	s_addc_u32 s31, s55, 0
	s_add_i32 s74, 0, 0x10000
	s_cmp_eq_u32 s7, s57
	s_cselect_b32 s63, s45, s31
	s_cselect_b32 s62, s44, s30
	s_cselect_b32 s31, s53, s15
	s_cselect_b32 s30, s52, s14
	s_add_i32 s57, 0, 0x14000
	v_add_u32_e32 v142, s74, v174
	v_add_u32_e32 v172, s57, v174
	ds_read_b128 v[130:133], v142
	ds_read_b128 v[134:137], v142 offset:1024
	ds_read_b128 v[138:141], v142 offset:2048
	ds_read_b128 v[142:145], v142 offset:3072
	ds_read_b128 v[168:171], v172
	ds_read_b128 v[178:181], v172 offset:1024
	ds_read_b128 v[182:185], v172 offset:2048
	ds_read_b128 v[186:189], v172 offset:3072
	v_lshl_add_u64 v[172:173], s[54:55], 0, v[166:167]
	s_add_i32 m0, s69, 0xc000
	ds_read_b128 v[190:193], v176
	ds_read_b128 v[194:197], v176 offset:1024
	ds_read_b128 v[202:205], v176 offset:2048
	ds_read_b128 v[206:209], v176 offset:3072
	ds_read_b128 v[210:213], v176 offset:4096
	ds_read_b128 v[228:231], v176 offset:5120
	ds_read_b128 v[232:235], v176 offset:6144
	ds_read_b128 v[236:239], v176 offset:7168
	global_load_lds_dwordx4 v[172:173], off
	v_lshl_add_u64 v[172:173], s[54:55], 0, v[164:165]
	s_add_i32 m0, s69, 0xe000
	s_nop 0
	global_load_lds_dwordx4 v[172:173], off
	s_waitcnt vmcnt(8)
	s_waitcnt lgkmcnt(0)
	s_barrier
	s_setprio 1
	s_waitcnt lgkmcnt(0)
	v_mfma_f32_16x16x32_bf16 v[126:129], v[130:133], v[190:193], v[126:129]
	v_mfma_f32_16x16x32_bf16 v[122:125], v[138:141], v[190:193], v[122:125]
	v_mfma_f32_16x16x32_bf16 v[114:117], v[130:133], v[202:205], v[114:117]
	v_mfma_f32_16x16x32_bf16 v[110:113], v[138:141], v[202:205], v[110:113]
	v_mfma_f32_16x16x32_bf16 v[98:101], v[130:133], v[210:213], v[98:101]
	v_mfma_f32_16x16x32_bf16 v[94:97], v[138:141], v[210:213], v[94:97]
	v_mfma_f32_16x16x32_bf16 v[82:85], v[130:133], v[232:235], v[82:85]
	v_mfma_f32_16x16x32_bf16 v[78:81], v[138:141], v[232:235], v[78:81]
	v_mfma_f32_16x16x32_bf16 v[126:129], v[134:137], v[194:197], v[126:129]
	v_mfma_f32_16x16x32_bf16 v[122:125], v[142:145], v[194:197], v[122:125]
	v_mfma_f32_16x16x32_bf16 v[114:117], v[134:137], v[206:209], v[114:117]
	v_mfma_f32_16x16x32_bf16 v[110:113], v[142:145], v[206:209], v[110:113]
	v_mfma_f32_16x16x32_bf16 v[98:101], v[134:137], v[228:231], v[98:101]
	v_mfma_f32_16x16x32_bf16 v[94:97], v[142:145], v[228:231], v[94:97]
	v_mfma_f32_16x16x32_bf16 v[82:85], v[134:137], v[236:239], v[82:85]
	v_mfma_f32_16x16x32_bf16 v[78:81], v[142:145], v[236:239], v[78:81]
	v_mfma_f32_16x16x32_bf16 v[118:121], v[168:171], v[190:193], v[118:121]
	v_mfma_f32_16x16x32_bf16 v[106:109], v[182:185], v[190:193], v[106:109]
	v_mfma_f32_16x16x32_bf16 v[102:105], v[168:171], v[202:205], v[102:105]
	v_mfma_f32_16x16x32_bf16 v[90:93], v[182:185], v[202:205], v[90:93]
	v_mfma_f32_16x16x32_bf16 v[86:89], v[168:171], v[210:213], v[86:89]
	v_mfma_f32_16x16x32_bf16 v[74:77], v[182:185], v[210:213], v[74:77]
	v_mfma_f32_16x16x32_bf16 v[70:73], v[168:171], v[232:235], v[70:73]
	v_mfma_f32_16x16x32_bf16 v[66:69], v[182:185], v[232:235], v[66:69]
	v_mfma_f32_16x16x32_bf16 v[118:121], v[178:181], v[194:197], v[118:121]
	v_mfma_f32_16x16x32_bf16 v[106:109], v[186:189], v[194:197], v[106:109]
	v_mfma_f32_16x16x32_bf16 v[102:105], v[178:181], v[206:209], v[102:105]
	v_mfma_f32_16x16x32_bf16 v[90:93], v[186:189], v[206:209], v[90:93]
	v_mfma_f32_16x16x32_bf16 v[86:89], v[178:181], v[228:231], v[86:89]
	v_mfma_f32_16x16x32_bf16 v[74:77], v[186:189], v[228:231], v[74:77]
	v_mfma_f32_16x16x32_bf16 v[70:73], v[178:181], v[236:239], v[70:73]
	v_mfma_f32_16x16x32_bf16 v[66:69], v[186:189], v[236:239], v[66:69]
	s_setprio 0
	s_barrier
	s_add_i32 s74, s74, s67
	v_lshl_add_u64 v[172:173], s[30:31], 0, v[0:1]
	s_mov_b32 m0, s74
	ds_read_b128 v[190:193], v176 offset:16384
	ds_read_b128 v[194:197], v176 offset:17408
	ds_read_b128 v[202:205], v176 offset:18432
	ds_read_b128 v[206:209], v176 offset:19456
	ds_read_b128 v[210:213], v176 offset:20480
	ds_read_b128 v[228:231], v176 offset:21504
	ds_read_b128 v[232:235], v176 offset:22528
	ds_read_b128 v[236:239], v176 offset:23552
	global_load_lds_dwordx4 v[172:173], off
	s_add_i32 m0, s74, 0x2000
	v_lshl_add_u64 v[198:199], s[30:31], 0, v[146:147]
	s_add_u32 s30, s30, s18
	s_addc_u32 s31, s31, 0
	s_add_i32 s57, s57, s67
	global_load_lds_dwordx4 v[198:199], off
	v_lshl_add_u64 v[214:215], s[30:31], 0, v[0:1]
	s_mov_b32 m0, s57
	v_lshl_add_u64 v[240:241], s[30:31], 0, v[146:147]
	global_load_lds_dwordx4 v[214:215], off
	s_add_i32 m0, s57, 0x2000
	v_lshl_add_u64 v[242:243], s[62:63], 0, v[0:1]
	global_load_lds_dwordx4 v[240:241], off
	s_mov_b32 m0, s69
	v_lshl_add_u64 v[244:245], s[62:63], 0, v[146:147]
	global_load_lds_dwordx4 v[242:243], off
	s_mov_b32 m0, s70
	s_nop 0
	global_load_lds_dwordx4 v[244:245], off
	s_waitcnt vmcnt(8)
	s_waitcnt lgkmcnt(0)
	s_barrier
; #define PG8_STAGE(bufoff, gbase, voff) do { _Pragma("unroll") for (int _i = 0; _i < 2; ++_i) \
;         __builtin_amdgcn_global_load_lds((const unsigned*)((const char*)(gbase) + (voff)[_i]), (LAS unsigned*)(lds + (bufoff) + ldsw + _i * 8192), 16, 0, 0); } while (0)
; #define PG8_LDA(dst, b, h) do { _Pragma("unroll") for (int m = 0; m < 4; ++m) _Pragma("unroll") for (int k = 0; k < 2; ++k) dst[m][k] = *(const LAS bf16x8*)(lds + PG8_SA(b, h) + aoff + m * 2048 + k * 1024); } while (0)
; #define PG8_LDB(dst, b, h) do { _Pragma("unroll") for (int n = 0; n < 2; ++n) _Pragma("unroll") for (int k = 0; k < 2; ++k) dst[n][k] = *(const LAS bf16x8*)(lds + PG8_SB(b, h) + boff + n * 2048 + k * 1024); } while (0)
; #define PG8_MMA(ai, bj, At, Bt) do { __builtin_amdgcn_s_setprio(1); _Pragma("unroll") for (int m = 0; m < 4; ++m) _Pragma("unroll") for (int n = 0; n < 2; ++n) _Pragma("unroll") for (int k = 0; k < 2; ++k) \
;         acc[ai][bj][m][n] = __builtin_amdgcn_mfma_f32_16x16x32_bf16(Bt[n][k], At[m][k], acc[ai][bj][m][n], 0, 0, 0); __builtin_amdgcn_s_setprio(0); } while (0)
; #define PG8_WAIT_V(n) asm volatile("s_waitcnt vmcnt(" #n ")" ::: "memory")
; #define PG8_WAIT_L(n) asm volatile("s_waitcnt lgkmcnt(" #n ")" ::: "memory")
; #define PG8_BAR __builtin_amdgcn_s_barrier()
; #define PG8_SCHED __builtin_amdgcn_sched_barrier(0)
; template <class Epi>
; __device__ __forceinline__ void gemm_phase(LAS unsigned char* lds, const Gemm g, const StaticOrder& S, const Epi& E) {
;     ...
;             PG8_WAIT_V(8); PG8_WAIT_L(0); PG8_BAR; PG8_MMA(1, 0, At, B0); PG8_MMA(1, 1, At, B1); PG8_BAR; PG8_SCHED;
;             PG8_LDB(B0, 1, 0); PG8_LDB(B1, 1, 1); PG8_SCHED; PG8_LDA(At, 1, 0); PG8_STAGE(PG8_SA(0, 1), a2 + hstepA, voffA);
;             PG8_WAIT_V(8); PG8_WAIT_L(0); PG8_BAR; PG8_MMA(0, 0, At, B0); PG8_MMA(0, 1, At, B1); PG8_BAR; PG8_SCHED;
	s_setprio 1
	s_waitcnt lgkmcnt(0)
	v_mfma_f32_16x16x32_bf16 v[62:65], v[130:133], v[190:193], v[62:65]
	v_mfma_f32_16x16x32_bf16 v[58:61], v[138:141], v[190:193], v[58:61]
	v_mfma_f32_16x16x32_bf16 v[50:53], v[130:133], v[202:205], v[50:53]
	v_mfma_f32_16x16x32_bf16 v[46:49], v[138:141], v[202:205], v[46:49]
	v_mfma_f32_16x16x32_bf16 v[34:37], v[130:133], v[210:213], v[34:37]
	v_mfma_f32_16x16x32_bf16 v[30:33], v[138:141], v[210:213], v[30:33]
	v_mfma_f32_16x16x32_bf16 v[18:21], v[130:133], v[232:235], v[18:21]
	v_mfma_f32_16x16x32_bf16 v[14:17], v[138:141], v[232:235], v[14:17]
	v_mfma_f32_16x16x32_bf16 v[62:65], v[134:137], v[194:197], v[62:65]
	v_mfma_f32_16x16x32_bf16 v[58:61], v[142:145], v[194:197], v[58:61]
	v_mfma_f32_16x16x32_bf16 v[50:53], v[134:137], v[206:209], v[50:53]
	v_mfma_f32_16x16x32_bf16 v[46:49], v[142:145], v[206:209], v[46:49]
	v_mfma_f32_16x16x32_bf16 v[34:37], v[134:137], v[228:231], v[34:37]
	v_mfma_f32_16x16x32_bf16 v[30:33], v[142:145], v[228:231], v[30:33]
	v_mfma_f32_16x16x32_bf16 v[18:21], v[134:137], v[236:239], v[18:21]
	v_mfma_f32_16x16x32_bf16 v[14:17], v[142:145], v[236:239], v[14:17]
	v_mfma_f32_16x16x32_bf16 v[54:57], v[168:171], v[190:193], v[54:57]
	v_mfma_f32_16x16x32_bf16 v[42:45], v[182:185], v[190:193], v[42:45]
	v_mfma_f32_16x16x32_bf16 v[38:41], v[168:171], v[202:205], v[38:41]
	v_mfma_f32_16x16x32_bf16 v[26:29], v[182:185], v[202:205], v[26:29]
	v_mfma_f32_16x16x32_bf16 v[22:25], v[168:171], v[210:213], v[22:25]
	v_mfma_f32_16x16x32_bf16 v[10:13], v[182:185], v[210:213], v[10:13]
	v_mfma_f32_16x16x32_bf16 v[6:9], v[168:171], v[232:235], v[6:9]
	v_mfma_f32_16x16x32_bf16 v[2:5], v[182:185], v[232:235], v[2:5]
	v_mfma_f32_16x16x32_bf16 v[54:57], v[178:181], v[194:197], v[54:57]
	v_mfma_f32_16x16x32_bf16 v[42:45], v[186:189], v[194:197], v[42:45]
	v_mfma_f32_16x16x32_bf16 v[38:41], v[178:181], v[206:209], v[38:41]
	v_mfma_f32_16x16x32_bf16 v[26:29], v[186:189], v[206:209], v[26:29]
	v_mfma_f32_16x16x32_bf16 v[22:25], v[178:181], v[228:231], v[22:25]
	v_mfma_f32_16x16x32_bf16 v[10:13], v[186:189], v[228:231], v[10:13]
	v_mfma_f32_16x16x32_bf16 v[6:9], v[178:181], v[236:239], v[6:9]
	v_mfma_f32_16x16x32_bf16 v[2:5], v[186:189], v[236:239], v[2:5]
	s_setprio 0
	s_barrier
	s_add_i32 s57, 0, 0x18000
	s_add_i32 s74, 0, 0x1c000
	v_add_u32_e32 v142, s57, v174
	v_add_u32_e32 v177, s74, v174
	ds_read_b128 v[130:133], v142
	ds_read_b128 v[134:137], v142 offset:1024
	ds_read_b128 v[138:141], v142 offset:2048
	ds_read_b128 v[142:145], v142 offset:3072
	ds_read_b128 v[168:171], v177
	ds_read_b128 v[178:181], v177 offset:1024
	ds_read_b128 v[182:185], v177 offset:2048
	ds_read_b128 v[186:189], v177 offset:3072
	s_add_u32 s30, s62, s18
	s_addc_u32 s31, s63, 0
	s_mov_b32 m0, s71
	v_lshl_add_u64 v[246:247], s[30:31], 0, v[0:1]
	ds_read_b128 v[190:193], v176 offset:32768
	ds_read_b128 v[194:197], v176 offset:33792
	ds_read_b128 v[202:205], v176 offset:34816
	ds_read_b128 v[206:209], v176 offset:35840
	ds_read_b128 v[210:213], v176 offset:36864
	ds_read_b128 v[228:231], v176 offset:37888
	ds_read_b128 v[232:235], v176 offset:38912
	ds_read_b128 v[236:239], v176 offset:39936
	global_load_lds_dwordx4 v[246:247], off
	v_lshl_add_u64 v[246:247], s[30:31], 0, v[146:147]
	s_mov_b32 m0, s92
	s_nop 0
	global_load_lds_dwordx4 v[246:247], off
	s_waitcnt vmcnt(8)
	s_waitcnt lgkmcnt(0)
	s_barrier
	s_setprio 1
	s_waitcnt lgkmcnt(0)
	v_mfma_f32_16x16x32_bf16 v[126:129], v[130:133], v[190:193], v[126:129]
	v_mfma_f32_16x16x32_bf16 v[122:125], v[138:141], v[190:193], v[122:125]
	v_mfma_f32_16x16x32_bf16 v[114:117], v[130:133], v[202:205], v[114:117]
	v_mfma_f32_16x16x32_bf16 v[110:113], v[138:141], v[202:205], v[110:113]
	v_mfma_f32_16x16x32_bf16 v[98:101], v[130:133], v[210:213], v[98:101]
	v_mfma_f32_16x16x32_bf16 v[94:97], v[138:141], v[210:213], v[94:97]
	v_mfma_f32_16x16x32_bf16 v[82:85], v[130:133], v[232:235], v[82:85]
	v_mfma_f32_16x16x32_bf16 v[78:81], v[138:141], v[232:235], v[78:81]
	v_mfma_f32_16x16x32_bf16 v[126:129], v[134:137], v[194:197], v[126:129]
	v_mfma_f32_16x16x32_bf16 v[122:125], v[142:145], v[194:197], v[122:125]
	v_mfma_f32_16x16x32_bf16 v[114:117], v[134:137], v[206:209], v[114:117]
	v_mfma_f32_16x16x32_bf16 v[110:113], v[142:145], v[206:209], v[110:113]
	v_mfma_f32_16x16x32_bf16 v[98:101], v[134:137], v[228:231], v[98:101]
	v_mfma_f32_16x16x32_bf16 v[94:97], v[142:145], v[228:231], v[94:97]
	v_mfma_f32_16x16x32_bf16 v[82:85], v[134:137], v[236:239], v[82:85]
	v_mfma_f32_16x16x32_bf16 v[78:81], v[142:145], v[236:239], v[78:81]
	v_mfma_f32_16x16x32_bf16 v[118:121], v[168:171], v[190:193], v[118:121]
	v_mfma_f32_16x16x32_bf16 v[106:109], v[182:185], v[190:193], v[106:109]
	v_mfma_f32_16x16x32_bf16 v[102:105], v[168:171], v[202:205], v[102:105]
	v_mfma_f32_16x16x32_bf16 v[90:93], v[182:185], v[202:205], v[90:93]
	v_mfma_f32_16x16x32_bf16 v[86:89], v[168:171], v[210:213], v[86:89]
	v_mfma_f32_16x16x32_bf16 v[74:77], v[182:185], v[210:213], v[74:77]
	v_mfma_f32_16x16x32_bf16 v[70:73], v[168:171], v[232:235], v[70:73]
	v_mfma_f32_16x16x32_bf16 v[66:69], v[182:185], v[232:235], v[66:69]
	v_mfma_f32_16x16x32_bf16 v[118:121], v[178:181], v[194:197], v[118:121]
	v_mfma_f32_16x16x32_bf16 v[106:109], v[186:189], v[194:197], v[106:109]
	v_mfma_f32_16x16x32_bf16 v[102:105], v[178:181], v[206:209], v[102:105]
	v_mfma_f32_16x16x32_bf16 v[90:93], v[186:189], v[206:209], v[90:93]
	v_mfma_f32_16x16x32_bf16 v[86:89], v[178:181], v[228:231], v[86:89]
	v_mfma_f32_16x16x32_bf16 v[74:77], v[186:189], v[228:231], v[74:77]
	v_mfma_f32_16x16x32_bf16 v[70:73], v[178:181], v[236:239], v[70:73]
	v_mfma_f32_16x16x32_bf16 v[66:69], v[186:189], v[236:239], v[66:69]
	s_setprio 0
	s_barrier
; #define PG8_STAGE(bufoff, gbase, voff) do { _Pragma("unroll") for (int _i = 0; _i < 2; ++_i) \
;         __builtin_amdgcn_global_load_lds((const unsigned*)((const char*)(gbase) + (voff)[_i]), (LAS unsigned*)(lds + (bufoff) + ldsw + _i * 8192), 16, 0, 0); } while (0)
; #define PG8_LDA(dst, b, h) do { _Pragma("unroll") for (int m = 0; m < 4; ++m) _Pragma("unroll") for (int k = 0; k < 2; ++k) dst[m][k] = *(const LAS bf16x8*)(lds + PG8_SA(b, h) + aoff + m * 2048 + k * 1024); } while (0)
; #define PG8_MMA(ai, bj, At, Bt) do { __builtin_amdgcn_s_setprio(1); _Pragma("unroll") for (int m = 0; m < 4; ++m) _Pragma("unroll") for (int n = 0; n < 2; ++n) _Pragma("unroll") for (int k = 0; k < 2; ++k) \
;         acc[ai][bj][m][n] = __builtin_amdgcn_mfma_f32_16x16x32_bf16(Bt[n][k], At[m][k], acc[ai][bj][m][n], 0, 0, 0); __builtin_amdgcn_s_setprio(0); } while (0)
; #define PG8_WAIT_V(n) asm volatile("s_waitcnt vmcnt(" #n ")" ::: "memory")
; #define PG8_WAIT_L(n) asm volatile("s_waitcnt lgkmcnt(" #n ")" ::: "memory")
; #define PG8_BAR __builtin_amdgcn_s_barrier()
; #define PG8_SCHED __builtin_amdgcn_sched_barrier(0)
; template <class Epi>
; __device__ __forceinline__ void gemm_phase(LAS unsigned char* lds, const Gemm g, const StaticOrder& S, const Epi& E) {
;     ...
;             PG8_LDA(At, 1, 1); PG8_STAGE(PG8_SB(1, 0), b3, voffB); PG8_STAGE(PG8_SB(1, 1), b3 + hstepB, voffB); PG8_STAGE(PG8_SA(1, 0), a3, voffA);
;             PG8_WAIT_V(8); PG8_WAIT_L(0); PG8_BAR; PG8_MMA(1, 0, At, B0); PG8_MMA(1, 1, At, B1); PG8_BAR; PG8_SCHED;
;         }
	s_add_i32 s30, s57, s67
	v_lshl_add_u64 v[172:173], v[172:173], 0, s[24:25]
	s_mov_b32 m0, s30
	ds_read_b128 v[190:193], v176 offset:49152
	ds_read_b128 v[194:197], v176 offset:50176
	ds_read_b128 v[202:205], v176 offset:51200
	ds_read_b128 v[206:209], v176 offset:52224
	ds_read_b128 v[210:213], v176 offset:53248
	ds_read_b128 v[228:231], v176 offset:54272
	ds_read_b128 v[232:235], v176 offset:55296
	ds_read_b128 v[236:239], v176 offset:56320
	global_load_lds_dwordx4 v[172:173], off
	v_lshl_add_u64 v[172:173], v[198:199], 0, s[24:25]
	s_add_i32 m0, s30, 0x2000
	s_add_i32 s30, s74, s67
	global_load_lds_dwordx4 v[172:173], off
	v_lshl_add_u64 v[172:173], v[214:215], 0, s[24:25]
	s_mov_b32 m0, s30
	s_nop 0
	global_load_lds_dwordx4 v[172:173], off
	v_lshl_add_u64 v[172:173], v[240:241], 0, s[24:25]
	s_add_i32 m0, s30, 0x2000
	s_nop 0
	global_load_lds_dwordx4 v[172:173], off
	v_lshl_add_u64 v[172:173], v[242:243], 0, s[24:25]
	s_mov_b32 m0, s97
	s_nop 0
	global_load_lds_dwordx4 v[172:173], off
	v_lshl_add_u64 v[172:173], v[244:245], 0, s[24:25]
	s_mov_b32 m0, s4
	s_nop 0
	global_load_lds_dwordx4 v[172:173], off
	s_waitcnt vmcnt(8)
	s_waitcnt lgkmcnt(0)
	s_barrier
	s_setprio 1
	s_waitcnt lgkmcnt(0)
	v_mfma_f32_16x16x32_bf16 v[62:65], v[130:133], v[190:193], v[62:65]
	v_mfma_f32_16x16x32_bf16 v[58:61], v[138:141], v[190:193], v[58:61]
	v_mfma_f32_16x16x32_bf16 v[50:53], v[130:133], v[202:205], v[50:53]
	v_mfma_f32_16x16x32_bf16 v[46:49], v[138:141], v[202:205], v[46:49]
	v_mfma_f32_16x16x32_bf16 v[34:37], v[130:133], v[210:213], v[34:37]
	v_mfma_f32_16x16x32_bf16 v[30:33], v[138:141], v[210:213], v[30:33]
	v_mfma_f32_16x16x32_bf16 v[18:21], v[130:133], v[232:235], v[18:21]
	v_mfma_f32_16x16x32_bf16 v[14:17], v[138:141], v[232:235], v[14:17]
	v_mfma_f32_16x16x32_bf16 v[62:65], v[134:137], v[194:197], v[62:65]
	v_mfma_f32_16x16x32_bf16 v[58:61], v[142:145], v[194:197], v[58:61]
	v_mfma_f32_16x16x32_bf16 v[50:53], v[134:137], v[206:209], v[50:53]
	v_mfma_f32_16x16x32_bf16 v[46:49], v[142:145], v[206:209], v[46:49]
	v_mfma_f32_16x16x32_bf16 v[34:37], v[134:137], v[228:231], v[34:37]
	v_mfma_f32_16x16x32_bf16 v[30:33], v[142:145], v[228:231], v[30:33]
	v_mfma_f32_16x16x32_bf16 v[18:21], v[134:137], v[236:239], v[18:21]
	v_mfma_f32_16x16x32_bf16 v[14:17], v[142:145], v[236:239], v[14:17]
	v_mfma_f32_16x16x32_bf16 v[54:57], v[168:171], v[190:193], v[54:57]
	v_mfma_f32_16x16x32_bf16 v[42:45], v[182:185], v[190:193], v[42:45]
	v_mfma_f32_16x16x32_bf16 v[38:41], v[168:171], v[202:205], v[38:41]
	v_mfma_f32_16x16x32_bf16 v[26:29], v[182:185], v[202:205], v[26:29]
	v_mfma_f32_16x16x32_bf16 v[22:25], v[168:171], v[210:213], v[22:25]
	v_mfma_f32_16x16x32_bf16 v[10:13], v[182:185], v[210:213], v[10:13]
	v_mfma_f32_16x16x32_bf16 v[6:9], v[168:171], v[232:235], v[6:9]
	v_mfma_f32_16x16x32_bf16 v[2:5], v[182:185], v[232:235], v[2:5]
	v_mfma_f32_16x16x32_bf16 v[54:57], v[178:181], v[194:197], v[54:57]
	v_mfma_f32_16x16x32_bf16 v[42:45], v[186:189], v[194:197], v[42:45]
	v_mfma_f32_16x16x32_bf16 v[38:41], v[178:181], v[206:209], v[38:41]
	v_mfma_f32_16x16x32_bf16 v[26:29], v[186:189], v[206:209], v[26:29]
	v_mfma_f32_16x16x32_bf16 v[22:25], v[178:181], v[228:231], v[22:25]
	v_mfma_f32_16x16x32_bf16 v[10:13], v[186:189], v[228:231], v[10:13]
	v_mfma_f32_16x16x32_bf16 v[6:9], v[178:181], v[236:239], v[6:9]
	v_mfma_f32_16x16x32_bf16 v[2:5], v[186:189], v[236:239], v[2:5]
	s_setprio 0
	s_barrier
	s_add_u32 s14, s14, 0x100
	s_addc_u32 s15, s15, 0
	s_add_u32 s54, s54, 0x100
	s_addc_u32 s55, s55, 0
	s_cmp_ge_u32 s58, s6
	s_mov_b32 s57, s58
	s_cbranch_scc0 .LBB0_227
	s_and_b64 vcc, exec, s[50:51]
	s_cbranch_vccz .LBB0_230
	s_barrier

; #define PG8_STAGE(bufoff, gbase, voff) do { _Pragma("unroll") for (int _i = 0; _i < 2; ++_i) \
;         __builtin_amdgcn_global_load_lds((const unsigned*)((const char*)(gbase) + (voff)[_i]), (LAS unsigned*)(lds + (bufoff) + ldsw + _i * 8192), 16, 0, 0); } while (0)
; #define PG8_LDA(dst, b, h) do { _Pragma("unroll") for (int m = 0; m < 4; ++m) _Pragma("unroll") for (int k = 0; k < 2; ++k) dst[m][k] = *(const LAS bf16x8*)(lds + PG8_SA(b, h) + aoff + m * 2048 + k * 1024); } while (0)
; #define PG8_LDB(dst, b, h) do { _Pragma("unroll") for (int n = 0; n < 2; ++n) _Pragma("unroll") for (int k = 0; k < 2; ++k) dst[n][k] = *(const LAS bf16x8*)(lds + PG8_SB(b, h) + boff + n * 2048 + k * 1024); } while (0)
; #define PG8_MMA(ai, bj, At, Bt) do { __builtin_amdgcn_s_setprio(1); _Pragma("unroll") for (int m = 0; m < 4; ++m) _Pragma("unroll") for (int n = 0; n < 2; ++n) _Pragma("unroll") for (int k = 0; k < 2; ++k) \
;         acc[ai][bj][m][n] = __builtin_amdgcn_mfma_f32_16x16x32_bf16(Bt[n][k], At[m][k], acc[ai][bj][m][n], 0, 0, 0); __builtin_amdgcn_s_setprio(0); } while (0)
; #define PG8_WAIT_V(n) asm volatile("s_waitcnt vmcnt(" #n ")" ::: "memory")
; #define PG8_WAIT_L(n) asm volatile("s_waitcnt lgkmcnt(" #n ")" ::: "memory")
; #define PG8_BAR __builtin_amdgcn_s_barrier()
; #define PG8_SCHED __builtin_amdgcn_sched_barrier(0)
; template <class Epi>
; __device__ __forceinline__ void gemm_phase(LAS unsigned char* lds, const Gemm g, const StaticOrder& S, const Epi& E) {
;     ...
;             PG8_LDB(B0, 0, 0); PG8_LDB(B1, 0, 1); PG8_SCHED; PG8_LDA(At, 0, 0); PG8_STAGE(PG8_SA(1, 1), a1 + hstepA, voffA);
;             PG8_WAIT_V(8); PG8_WAIT_L(0); PG8_BAR; PG8_MMA(0, 0, At, B0); PG8_MMA(0, 1, At, B1); PG8_BAR; PG8_SCHED;
;             PG8_LDA(At, 0, 1); PG8_STAGE(PG8_SB(0, 0), b2, voffB); PG8_STAGE(PG8_SB(0, 1), b2 + hstepB, voffB); PG8_STAGE(PG8_SA(0, 0), a2, voffA);
;             PG8_WAIT_V(8); PG8_WAIT_L(0); PG8_BAR; PG8_MMA(1, 0, At, B0); PG8_MMA(1, 1, At, B1); PG8_BAR; PG8_SCHED;
.LBB0_256:
	s_add_i32 s46, s44, 2
	s_add_u32 s30, s40, 0x80
	s_addc_u32 s31, s41, 0
	s_add_i32 s47, 0, 0x10000
	s_cmp_eq_u32 s53, s44
	s_cselect_b32 s45, s9, s31
	s_cselect_b32 s44, s8, s30
	s_cselect_b32 s31, s13, s63
	s_cselect_b32 s30, s12, s62
	s_add_i32 s66, 0, 0x14000
	v_add_u32_e32 v162, s47, v148
	v_add_u32_e32 v178, s66, v148
	ds_read_b128 v[150:153], v162
	ds_read_b128 v[154:157], v162 offset:1024
	ds_read_b128 v[158:161], v162 offset:2048
	ds_read_b128 v[162:165], v162 offset:3072
	ds_read_b128 v[166:169], v178
	ds_read_b128 v[170:173], v178 offset:1024
	ds_read_b128 v[174:177], v178 offset:2048
	ds_read_b128 v[178:181], v178 offset:3072
	v_lshl_add_u64 v[198:199], s[40:41], 0, v[146:147]
	s_add_i32 m0, s11, 0xc000
	ds_read_b128 v[182:185], v149
	ds_read_b128 v[186:189], v149 offset:1024
	ds_read_b128 v[190:193], v149 offset:2048
	ds_read_b128 v[194:197], v149 offset:3072
	ds_read_b128 v[202:205], v149 offset:4096
	ds_read_b128 v[206:209], v149 offset:5120
	ds_read_b128 v[210:213], v149 offset:6144
	ds_read_b128 v[228:231], v149 offset:7168
	global_load_lds_dwordx4 v[198:199], off
	v_lshl_add_u64 v[198:199], s[40:41], 0, v[144:145]
	s_add_i32 m0, s11, 0xe000
	s_nop 0
	global_load_lds_dwordx4 v[198:199], off
	s_waitcnt vmcnt(8)
	s_waitcnt lgkmcnt(0)
	s_barrier
	s_setprio 1
	s_waitcnt lgkmcnt(0)
	v_mfma_f32_16x16x32_bf16 v[126:129], v[150:153], v[182:185], v[126:129]
	v_mfma_f32_16x16x32_bf16 v[122:125], v[158:161], v[182:185], v[122:125]
	v_mfma_f32_16x16x32_bf16 v[118:121], v[150:153], v[190:193], v[118:121]
	v_mfma_f32_16x16x32_bf16 v[114:117], v[158:161], v[190:193], v[114:117]
	v_mfma_f32_16x16x32_bf16 v[106:109], v[150:153], v[202:205], v[106:109]
	v_mfma_f32_16x16x32_bf16 v[98:101], v[158:161], v[202:205], v[98:101]
	v_mfma_f32_16x16x32_bf16 v[90:93], v[150:153], v[210:213], v[90:93]
	v_mfma_f32_16x16x32_bf16 v[82:85], v[158:161], v[210:213], v[82:85]
	v_mfma_f32_16x16x32_bf16 v[126:129], v[154:157], v[186:189], v[126:129]
	v_mfma_f32_16x16x32_bf16 v[122:125], v[162:165], v[186:189], v[122:125]
	v_mfma_f32_16x16x32_bf16 v[118:121], v[154:157], v[194:197], v[118:121]
	v_mfma_f32_16x16x32_bf16 v[114:117], v[162:165], v[194:197], v[114:117]
	v_mfma_f32_16x16x32_bf16 v[106:109], v[154:157], v[206:209], v[106:109]
	v_mfma_f32_16x16x32_bf16 v[98:101], v[162:165], v[206:209], v[98:101]
	v_mfma_f32_16x16x32_bf16 v[90:93], v[154:157], v[228:231], v[90:93]
	v_mfma_f32_16x16x32_bf16 v[82:85], v[162:165], v[228:231], v[82:85]
	v_mfma_f32_16x16x32_bf16 v[110:113], v[166:169], v[182:185], v[110:113]
	v_mfma_f32_16x16x32_bf16 v[102:105], v[174:177], v[182:185], v[102:105]
	v_mfma_f32_16x16x32_bf16 v[94:97], v[166:169], v[190:193], v[94:97]
	v_mfma_f32_16x16x32_bf16 v[86:89], v[174:177], v[190:193], v[86:89]
	v_mfma_f32_16x16x32_bf16 v[78:81], v[166:169], v[202:205], v[78:81]
	v_mfma_f32_16x16x32_bf16 v[74:77], v[174:177], v[202:205], v[74:77]
	v_mfma_f32_16x16x32_bf16 v[70:73], v[166:169], v[210:213], v[70:73]
	v_mfma_f32_16x16x32_bf16 v[66:69], v[174:177], v[210:213], v[66:69]
	v_mfma_f32_16x16x32_bf16 v[110:113], v[170:173], v[186:189], v[110:113]
	v_mfma_f32_16x16x32_bf16 v[102:105], v[178:181], v[186:189], v[102:105]
	v_mfma_f32_16x16x32_bf16 v[94:97], v[170:173], v[194:197], v[94:97]
	v_mfma_f32_16x16x32_bf16 v[86:89], v[178:181], v[194:197], v[86:89]
	v_mfma_f32_16x16x32_bf16 v[78:81], v[170:173], v[206:209], v[78:81]
	v_mfma_f32_16x16x32_bf16 v[74:77], v[178:181], v[206:209], v[74:77]
	v_mfma_f32_16x16x32_bf16 v[70:73], v[170:173], v[228:231], v[70:73]
	v_mfma_f32_16x16x32_bf16 v[66:69], v[178:181], v[228:231], v[66:69]
	s_setprio 0
	s_barrier
	s_add_i32 s47, s47, s5
	v_lshl_add_u64 v[198:199], s[30:31], 0, v[0:1]
	s_mov_b32 m0, s47
	ds_read_b128 v[182:185], v149 offset:16384
	ds_read_b128 v[186:189], v149 offset:17408
	ds_read_b128 v[190:193], v149 offset:18432
	ds_read_b128 v[194:197], v149 offset:19456
	ds_read_b128 v[202:205], v149 offset:20480
	ds_read_b128 v[206:209], v149 offset:21504
	ds_read_b128 v[210:213], v149 offset:22528
	ds_read_b128 v[228:231], v149 offset:23552
	global_load_lds_dwordx4 v[198:199], off
	s_add_i32 m0, s47, 0x2000
	v_lshl_add_u64 v[214:215], s[30:31], 0, v[130:131]
	s_add_u32 s30, s30, s18
	s_addc_u32 s31, s31, 0
	s_add_i32 s47, s66, s5
	global_load_lds_dwordx4 v[214:215], off
	v_lshl_add_u64 v[232:233], s[30:31], 0, v[0:1]
	s_mov_b32 m0, s47
	v_lshl_add_u64 v[234:235], s[30:31], 0, v[130:131]
	global_load_lds_dwordx4 v[232:233], off
	s_add_i32 m0, s47, 0x2000
	v_lshl_add_u64 v[236:237], s[44:45], 0, v[0:1]
	global_load_lds_dwordx4 v[234:235], off
	s_mov_b32 m0, s11
	v_lshl_add_u64 v[238:239], s[44:45], 0, v[130:131]
	global_load_lds_dwordx4 v[236:237], off
	s_mov_b32 m0, s16
	s_nop 0
	global_load_lds_dwordx4 v[238:239], off
	s_waitcnt vmcnt(8)
	s_waitcnt lgkmcnt(0)
	s_barrier
; #define PG8_STAGE(bufoff, gbase, voff) do { _Pragma("unroll") for (int _i = 0; _i < 2; ++_i) \
;         __builtin_amdgcn_global_load_lds((const unsigned*)((const char*)(gbase) + (voff)[_i]), (LAS unsigned*)(lds + (bufoff) + ldsw + _i * 8192), 16, 0, 0); } while (0)
; #define PG8_LDA(dst, b, h) do { _Pragma("unroll") for (int m = 0; m < 4; ++m) _Pragma("unroll") for (int k = 0; k < 2; ++k) dst[m][k] = *(const LAS bf16x8*)(lds + PG8_SA(b, h) + aoff + m * 2048 + k * 1024); } while (0)
; #define PG8_LDB(dst, b, h) do { _Pragma("unroll") for (int n = 0; n < 2; ++n) _Pragma("unroll") for (int k = 0; k < 2; ++k) dst[n][k] = *(const LAS bf16x8*)(lds + PG8_SB(b, h) + boff + n * 2048 + k * 1024); } while (0)
; #define PG8_MMA(ai, bj, At, Bt) do { __builtin_amdgcn_s_setprio(1); _Pragma("unroll") for (int m = 0; m < 4; ++m) _Pragma("unroll") for (int n = 0; n < 2; ++n) _Pragma("unroll") for (int k = 0; k < 2; ++k) \
;         acc[ai][bj][m][n] = __builtin_amdgcn_mfma_f32_16x16x32_bf16(Bt[n][k], At[m][k], acc[ai][bj][m][n], 0, 0, 0); __builtin_amdgcn_s_setprio(0); } while (0)
; #define PG8_WAIT_V(n) asm volatile("s_waitcnt vmcnt(" #n ")" ::: "memory")
; #define PG8_WAIT_L(n) asm volatile("s_waitcnt lgkmcnt(" #n ")" ::: "memory")
; #define PG8_BAR __builtin_amdgcn_s_barrier()
; #define PG8_SCHED __builtin_amdgcn_sched_barrier(0)
; template <class Epi>
; __device__ __forceinline__ void gemm_phase(LAS unsigned char* lds, const Gemm g, const StaticOrder& S, const Epi& E) {
;     ...
;             PG8_WAIT_V(8); PG8_WAIT_L(0); PG8_BAR; PG8_MMA(1, 0, At, B0); PG8_MMA(1, 1, At, B1); PG8_BAR; PG8_SCHED;
;             PG8_LDB(B0, 1, 0); PG8_LDB(B1, 1, 1); PG8_SCHED; PG8_LDA(At, 1, 0); PG8_STAGE(PG8_SA(0, 1), a2 + hstepA, voffA);
;             PG8_WAIT_V(8); PG8_WAIT_L(0); PG8_BAR; PG8_MMA(0, 0, At, B0); PG8_MMA(0, 1, At, B1); PG8_BAR; PG8_SCHED;
	s_setprio 1
	s_waitcnt lgkmcnt(0)
	v_mfma_f32_16x16x32_bf16 v[62:65], v[150:153], v[182:185], v[62:65]
	v_mfma_f32_16x16x32_bf16 v[58:61], v[158:161], v[182:185], v[58:61]
	v_mfma_f32_16x16x32_bf16 v[54:57], v[150:153], v[190:193], v[54:57]
	v_mfma_f32_16x16x32_bf16 v[50:53], v[158:161], v[190:193], v[50:53]
	v_mfma_f32_16x16x32_bf16 v[46:49], v[150:153], v[202:205], v[46:49]
	v_mfma_f32_16x16x32_bf16 v[42:45], v[158:161], v[202:205], v[42:45]
	v_mfma_f32_16x16x32_bf16 v[34:37], v[150:153], v[210:213], v[34:37]
	v_mfma_f32_16x16x32_bf16 v[26:29], v[158:161], v[210:213], v[26:29]
	v_mfma_f32_16x16x32_bf16 v[62:65], v[154:157], v[186:189], v[62:65]
	v_mfma_f32_16x16x32_bf16 v[58:61], v[162:165], v[186:189], v[58:61]
	v_mfma_f32_16x16x32_bf16 v[54:57], v[154:157], v[194:197], v[54:57]
	v_mfma_f32_16x16x32_bf16 v[50:53], v[162:165], v[194:197], v[50:53]
	v_mfma_f32_16x16x32_bf16 v[46:49], v[154:157], v[206:209], v[46:49]
	v_mfma_f32_16x16x32_bf16 v[42:45], v[162:165], v[206:209], v[42:45]
	v_mfma_f32_16x16x32_bf16 v[34:37], v[154:157], v[228:231], v[34:37]
	v_mfma_f32_16x16x32_bf16 v[26:29], v[162:165], v[228:231], v[26:29]
	v_mfma_f32_16x16x32_bf16 v[38:41], v[166:169], v[182:185], v[38:41]
	v_mfma_f32_16x16x32_bf16 v[30:33], v[174:177], v[182:185], v[30:33]
	v_mfma_f32_16x16x32_bf16 v[22:25], v[166:169], v[190:193], v[22:25]
	v_mfma_f32_16x16x32_bf16 v[18:21], v[174:177], v[190:193], v[18:21]
	v_mfma_f32_16x16x32_bf16 v[14:17], v[166:169], v[202:205], v[14:17]
	v_mfma_f32_16x16x32_bf16 v[10:13], v[174:177], v[202:205], v[10:13]
	v_mfma_f32_16x16x32_bf16 v[6:9], v[166:169], v[210:213], v[6:9]
	v_mfma_f32_16x16x32_bf16 v[2:5], v[174:177], v[210:213], v[2:5]
	v_mfma_f32_16x16x32_bf16 v[38:41], v[170:173], v[186:189], v[38:41]
	v_mfma_f32_16x16x32_bf16 v[30:33], v[178:181], v[186:189], v[30:33]
	v_mfma_f32_16x16x32_bf16 v[22:25], v[170:173], v[194:197], v[22:25]
	v_mfma_f32_16x16x32_bf16 v[18:21], v[178:181], v[194:197], v[18:21]
	v_mfma_f32_16x16x32_bf16 v[14:17], v[170:173], v[206:209], v[14:17]
	v_mfma_f32_16x16x32_bf16 v[10:13], v[178:181], v[206:209], v[10:13]
	v_mfma_f32_16x16x32_bf16 v[6:9], v[170:173], v[228:231], v[6:9]
	v_mfma_f32_16x16x32_bf16 v[2:5], v[178:181], v[228:231], v[2:5]
	s_setprio 0
	s_barrier
	s_add_i32 s47, 0, 0x18000
	s_add_i32 s66, 0, 0x1c000
	v_add_u32_e32 v162, s47, v148
	v_add_u32_e32 v178, s66, v148
	ds_read_b128 v[150:153], v162
	ds_read_b128 v[154:157], v162 offset:1024
	ds_read_b128 v[158:161], v162 offset:2048
	ds_read_b128 v[162:165], v162 offset:3072
	ds_read_b128 v[166:169], v178
	ds_read_b128 v[170:173], v178 offset:1024
	ds_read_b128 v[174:177], v178 offset:2048
	ds_read_b128 v[178:181], v178 offset:3072
	s_add_u32 s30, s44, s18
	s_addc_u32 s31, s45, 0
	s_mov_b32 m0, s48
	v_lshl_add_u64 v[240:241], s[30:31], 0, v[0:1]
	ds_read_b128 v[182:185], v149 offset:32768
	ds_read_b128 v[186:189], v149 offset:33792
	ds_read_b128 v[190:193], v149 offset:34816
	ds_read_b128 v[194:197], v149 offset:35840
	ds_read_b128 v[202:205], v149 offset:36864
	ds_read_b128 v[206:209], v149 offset:37888
	ds_read_b128 v[210:213], v149 offset:38912
	ds_read_b128 v[228:231], v149 offset:39936
	global_load_lds_dwordx4 v[240:241], off
	v_lshl_add_u64 v[240:241], s[30:31], 0, v[130:131]
	s_mov_b32 m0, s49
	s_nop 0
	global_load_lds_dwordx4 v[240:241], off
	s_waitcnt vmcnt(8)
	s_waitcnt lgkmcnt(0)
	s_barrier
	s_setprio 1
	s_waitcnt lgkmcnt(0)
	v_mfma_f32_16x16x32_bf16 v[126:129], v[150:153], v[182:185], v[126:129]
	v_mfma_f32_16x16x32_bf16 v[122:125], v[158:161], v[182:185], v[122:125]
	v_mfma_f32_16x16x32_bf16 v[118:121], v[150:153], v[190:193], v[118:121]
	v_mfma_f32_16x16x32_bf16 v[114:117], v[158:161], v[190:193], v[114:117]
	v_mfma_f32_16x16x32_bf16 v[106:109], v[150:153], v[202:205], v[106:109]
	v_mfma_f32_16x16x32_bf16 v[98:101], v[158:161], v[202:205], v[98:101]
	v_mfma_f32_16x16x32_bf16 v[90:93], v[150:153], v[210:213], v[90:93]
	v_mfma_f32_16x16x32_bf16 v[82:85], v[158:161], v[210:213], v[82:85]
	v_mfma_f32_16x16x32_bf16 v[126:129], v[154:157], v[186:189], v[126:129]
	v_mfma_f32_16x16x32_bf16 v[122:125], v[162:165], v[186:189], v[122:125]
	v_mfma_f32_16x16x32_bf16 v[118:121], v[154:157], v[194:197], v[118:121]
	v_mfma_f32_16x16x32_bf16 v[114:117], v[162:165], v[194:197], v[114:117]
	v_mfma_f32_16x16x32_bf16 v[106:109], v[154:157], v[206:209], v[106:109]
	v_mfma_f32_16x16x32_bf16 v[98:101], v[162:165], v[206:209], v[98:101]
	v_mfma_f32_16x16x32_bf16 v[90:93], v[154:157], v[228:231], v[90:93]
	v_mfma_f32_16x16x32_bf16 v[82:85], v[162:165], v[228:231], v[82:85]
	v_mfma_f32_16x16x32_bf16 v[110:113], v[166:169], v[182:185], v[110:113]
	v_mfma_f32_16x16x32_bf16 v[102:105], v[174:177], v[182:185], v[102:105]
	v_mfma_f32_16x16x32_bf16 v[94:97], v[166:169], v[190:193], v[94:97]
	v_mfma_f32_16x16x32_bf16 v[86:89], v[174:177], v[190:193], v[86:89]
	v_mfma_f32_16x16x32_bf16 v[78:81], v[166:169], v[202:205], v[78:81]
	v_mfma_f32_16x16x32_bf16 v[74:77], v[174:177], v[202:205], v[74:77]
	v_mfma_f32_16x16x32_bf16 v[70:73], v[166:169], v[210:213], v[70:73]
	v_mfma_f32_16x16x32_bf16 v[66:69], v[174:177], v[210:213], v[66:69]
	v_mfma_f32_16x16x32_bf16 v[110:113], v[170:173], v[186:189], v[110:113]
	v_mfma_f32_16x16x32_bf16 v[102:105], v[178:181], v[186:189], v[102:105]
	v_mfma_f32_16x16x32_bf16 v[94:97], v[170:173], v[194:197], v[94:97]
	v_mfma_f32_16x16x32_bf16 v[86:89], v[178:181], v[194:197], v[86:89]
	v_mfma_f32_16x16x32_bf16 v[78:81], v[170:173], v[206:209], v[78:81]
	v_mfma_f32_16x16x32_bf16 v[74:77], v[178:181], v[206:209], v[74:77]
	v_mfma_f32_16x16x32_bf16 v[70:73], v[170:173], v[228:231], v[70:73]
	v_mfma_f32_16x16x32_bf16 v[66:69], v[178:181], v[228:231], v[66:69]
	s_setprio 0
	s_barrier
; #define PG8_STAGE(bufoff, gbase, voff) do { _Pragma("unroll") for (int _i = 0; _i < 2; ++_i) \
;         __builtin_amdgcn_global_load_lds((const unsigned*)((const char*)(gbase) + (voff)[_i]), (LAS unsigned*)(lds + (bufoff) + ldsw + _i * 8192), 16, 0, 0); } while (0)
; #define PG8_LDA(dst, b, h) do { _Pragma("unroll") for (int m = 0; m < 4; ++m) _Pragma("unroll") for (int k = 0; k < 2; ++k) dst[m][k] = *(const LAS bf16x8*)(lds + PG8_SA(b, h) + aoff + m * 2048 + k * 1024); } while (0)
; #define PG8_MMA(ai, bj, At, Bt) do { __builtin_amdgcn_s_setprio(1); _Pragma("unroll") for (int m = 0; m < 4; ++m) _Pragma("unroll") for (int n = 0; n < 2; ++n) _Pragma("unroll") for (int k = 0; k < 2; ++k) \
;         acc[ai][bj][m][n] = __builtin_amdgcn_mfma_f32_16x16x32_bf16(Bt[n][k], At[m][k], acc[ai][bj][m][n], 0, 0, 0); __builtin_amdgcn_s_setprio(0); } while (0)
; #define PG8_WAIT_V(n) asm volatile("s_waitcnt vmcnt(" #n ")" ::: "memory")
; #define PG8_WAIT_L(n) asm volatile("s_waitcnt lgkmcnt(" #n ")" ::: "memory")
; #define PG8_BAR __builtin_amdgcn_s_barrier()
; #define PG8_SCHED __builtin_amdgcn_sched_barrier(0)
; template <class Epi>
; __device__ __forceinline__ void gemm_phase(LAS unsigned char* lds, const Gemm g, const StaticOrder& S, const Epi& E) {
;     ...
;             PG8_LDA(At, 1, 1); PG8_STAGE(PG8_SB(1, 0), b3, voffB); PG8_STAGE(PG8_SB(1, 1), b3 + hstepB, voffB); PG8_STAGE(PG8_SA(1, 0), a3, voffA);
;             PG8_WAIT_V(8); PG8_WAIT_L(0); PG8_BAR; PG8_MMA(1, 0, At, B0); PG8_MMA(1, 1, At, B1); PG8_BAR; PG8_SCHED;
;         }
	s_add_i32 s30, s47, s5
	v_lshl_add_u64 v[198:199], v[198:199], 0, s[24:25]
	s_mov_b32 m0, s30
	ds_read_b128 v[182:185], v149 offset:49152
	ds_read_b128 v[186:189], v149 offset:50176
	ds_read_b128 v[190:193], v149 offset:51200
	ds_read_b128 v[194:197], v149 offset:52224
	ds_read_b128 v[202:205], v149 offset:53248
	ds_read_b128 v[206:209], v149 offset:54272
	ds_read_b128 v[210:213], v149 offset:55296
	ds_read_b128 v[228:231], v149 offset:56320
	global_load_lds_dwordx4 v[198:199], off
	v_lshl_add_u64 v[198:199], v[214:215], 0, s[24:25]
	s_add_i32 m0, s30, 0x2000
	s_add_i32 s30, s66, s5
	global_load_lds_dwordx4 v[198:199], off
	v_lshl_add_u64 v[198:199], v[232:233], 0, s[24:25]
	s_mov_b32 m0, s30
	s_nop 0
	global_load_lds_dwordx4 v[198:199], off
	v_lshl_add_u64 v[198:199], v[234:235], 0, s[24:25]
	s_add_i32 m0, s30, 0x2000
	s_nop 0
	global_load_lds_dwordx4 v[198:199], off
	v_lshl_add_u64 v[198:199], v[236:237], 0, s[24:25]
	s_mov_b32 m0, s51
	s_nop 0
	global_load_lds_dwordx4 v[198:199], off
	v_lshl_add_u64 v[198:199], v[238:239], 0, s[24:25]
	s_mov_b32 m0, s52
	s_nop 0
	global_load_lds_dwordx4 v[198:199], off
	s_waitcnt vmcnt(8)
	s_waitcnt lgkmcnt(0)
	s_barrier
	s_setprio 1
	s_waitcnt lgkmcnt(0)
	v_mfma_f32_16x16x32_bf16 v[62:65], v[150:153], v[182:185], v[62:65]
	v_mfma_f32_16x16x32_bf16 v[58:61], v[158:161], v[182:185], v[58:61]
	v_mfma_f32_16x16x32_bf16 v[54:57], v[150:153], v[190:193], v[54:57]
	v_mfma_f32_16x16x32_bf16 v[50:53], v[158:161], v[190:193], v[50:53]
	v_mfma_f32_16x16x32_bf16 v[46:49], v[150:153], v[202:205], v[46:49]
	v_mfma_f32_16x16x32_bf16 v[42:45], v[158:161], v[202:205], v[42:45]
	v_mfma_f32_16x16x32_bf16 v[34:37], v[150:153], v[210:213], v[34:37]
	v_mfma_f32_16x16x32_bf16 v[26:29], v[158:161], v[210:213], v[26:29]
	v_mfma_f32_16x16x32_bf16 v[62:65], v[154:157], v[186:189], v[62:65]
	v_mfma_f32_16x16x32_bf16 v[58:61], v[162:165], v[186:189], v[58:61]
	v_mfma_f32_16x16x32_bf16 v[54:57], v[154:157], v[194:197], v[54:57]
	v_mfma_f32_16x16x32_bf16 v[50:53], v[162:165], v[194:197], v[50:53]
	v_mfma_f32_16x16x32_bf16 v[46:49], v[154:157], v[206:209], v[46:49]
	v_mfma_f32_16x16x32_bf16 v[42:45], v[162:165], v[206:209], v[42:45]
	v_mfma_f32_16x16x32_bf16 v[34:37], v[154:157], v[228:231], v[34:37]
	v_mfma_f32_16x16x32_bf16 v[26:29], v[162:165], v[228:231], v[26:29]
	v_mfma_f32_16x16x32_bf16 v[38:41], v[166:169], v[182:185], v[38:41]
	v_mfma_f32_16x16x32_bf16 v[30:33], v[174:177], v[182:185], v[30:33]
	v_mfma_f32_16x16x32_bf16 v[22:25], v[166:169], v[190:193], v[22:25]
	v_mfma_f32_16x16x32_bf16 v[18:21], v[174:177], v[190:193], v[18:21]
	v_mfma_f32_16x16x32_bf16 v[14:17], v[166:169], v[202:205], v[14:17]
	v_mfma_f32_16x16x32_bf16 v[10:13], v[174:177], v[202:205], v[10:13]
	v_mfma_f32_16x16x32_bf16 v[6:9], v[166:169], v[210:213], v[6:9]
	v_mfma_f32_16x16x32_bf16 v[2:5], v[174:177], v[210:213], v[2:5]
	v_mfma_f32_16x16x32_bf16 v[38:41], v[170:173], v[186:189], v[38:41]
	v_mfma_f32_16x16x32_bf16 v[30:33], v[178:181], v[186:189], v[30:33]
	v_mfma_f32_16x16x32_bf16 v[22:25], v[170:173], v[194:197], v[22:25]
	v_mfma_f32_16x16x32_bf16 v[18:21], v[178:181], v[194:197], v[18:21]
	v_mfma_f32_16x16x32_bf16 v[14:17], v[170:173], v[206:209], v[14:17]
	v_mfma_f32_16x16x32_bf16 v[10:13], v[178:181], v[206:209], v[10:13]
	v_mfma_f32_16x16x32_bf16 v[6:9], v[170:173], v[228:231], v[6:9]
	v_mfma_f32_16x16x32_bf16 v[2:5], v[178:181], v[228:231], v[2:5]
	s_setprio 0
	s_barrier
	s_add_u32 s62, s62, 0x100
	s_addc_u32 s63, s63, 0
	s_add_u32 s40, s40, 0x100
	s_addc_u32 s41, s41, 0
	s_cmp_ge_u32 s46, s50
	s_mov_b32 s44, s46
	s_cbranch_scc0 .LBB0_256
	s_and_b64 vcc, exec, s[42:43]
	s_cbranch_vccz .LBB0_259
	s_barrier

; #define PG8_STAGE(bufoff, gbase, voff) do { _Pragma("unroll") for (int _i = 0; _i < 2; ++_i) \
;         __builtin_amdgcn_global_load_lds((const unsigned*)((const char*)(gbase) + (voff)[_i]), (LAS unsigned*)(lds + (bufoff) + ldsw + _i * 8192), 16, 0, 0); } while (0)
; #define PG8_LDA(dst, b, h) do { _Pragma("unroll") for (int m = 0; m < 4; ++m) _Pragma("unroll") for (int k = 0; k < 2; ++k) dst[m][k] = *(const LAS bf16x8*)(lds + PG8_SA(b, h) + aoff + m * 2048 + k * 1024); } while (0)
; #define PG8_LDB(dst, b, h) do { _Pragma("unroll") for (int n = 0; n < 2; ++n) _Pragma("unroll") for (int k = 0; k < 2; ++k) dst[n][k] = *(const LAS bf16x8*)(lds + PG8_SB(b, h) + boff + n * 2048 + k * 1024); } while (0)
; #define PG8_MMA(ai, bj, At, Bt) do { __builtin_amdgcn_s_setprio(1); _Pragma("unroll") for (int m = 0; m < 4; ++m) _Pragma("unroll") for (int n = 0; n < 2; ++n) _Pragma("unroll") for (int k = 0; k < 2; ++k) \
;         acc[ai][bj][m][n] = __builtin_amdgcn_mfma_f32_16x16x32_bf16(Bt[n][k], At[m][k], acc[ai][bj][m][n], 0, 0, 0); __builtin_amdgcn_s_setprio(0); } while (0)
; #define PG8_WAIT_V(n) asm volatile("s_waitcnt vmcnt(" #n ")" ::: "memory")
; #define PG8_WAIT_L(n) asm volatile("s_waitcnt lgkmcnt(" #n ")" ::: "memory")
; #define PG8_BAR __builtin_amdgcn_s_barrier()
; #define PG8_SCHED __builtin_amdgcn_sched_barrier(0)
; template <class Epi>
; __device__ __forceinline__ void gemm_phase(LAS unsigned char* lds, const Gemm g, const StaticOrder& S, const Epi& E) {
;     ...
;             PG8_LDB(B0, 0, 0); PG8_LDB(B1, 0, 1); PG8_SCHED; PG8_LDA(At, 0, 0); PG8_STAGE(PG8_SA(1, 1), a1 + hstepA, voffA);
;             PG8_WAIT_V(8); PG8_WAIT_L(0); PG8_BAR; PG8_MMA(0, 0, At, B0); PG8_MMA(0, 1, At, B1); PG8_BAR; PG8_SCHED;
;             PG8_LDA(At, 0, 1); PG8_STAGE(PG8_SB(0, 0), b2, voffB); PG8_STAGE(PG8_SB(0, 1), b2 + hstepB, voffB); PG8_STAGE(PG8_SA(0, 0), a2, voffA);
;             PG8_WAIT_V(8); PG8_WAIT_L(0); PG8_BAR; PG8_MMA(1, 0, At, B0); PG8_MMA(1, 1, At, B1); PG8_BAR; PG8_SCHED;
.LBB0_292:
	s_add_i32 vcc_lo, s72, 2
	s_add_u32 s30, s62, 0x80
	s_addc_u32 s31, s63, 0
	s_add_i32 vcc_hi, 0, 0x10000
	s_cmp_eq_u32 s7, s72
	s_cselect_b32 s73, s41, s31
	s_cselect_b32 s72, s40, s30
	v_add_u32_e32 v140, vcc_hi, v143
	s_cselect_b32 s31, s55, s15
	s_cselect_b32 s30, s54, s14
	s_add_i32 s77, 0, 0x14000
	ds_read_b128 v[146:149], v140
	ds_read_b128 v[150:153], v140 offset:1024
	ds_read_b128 v[154:157], v140 offset:2048
	ds_read_b128 v[158:161], v140 offset:3072
	v_add_u32_e32 v140, s77, v143
	ds_read_b128 v[162:165], v140
	ds_read_b128 v[166:169], v140 offset:1024
	ds_read_b128 v[170:173], v140 offset:2048
	ds_read_b128 v[174:177], v140 offset:3072
	v_lshl_add_u64 v[140:141], s[62:63], 0, v[138:139]
	s_add_i32 m0, s96, 0xc000
	ds_read_b128 v[178:181], v145
	ds_read_b128 v[182:185], v145 offset:1024
	ds_read_b128 v[186:189], v145 offset:2048
	ds_read_b128 v[190:193], v145 offset:3072
	ds_read_b128 v[202:205], v145 offset:4096
	ds_read_b128 v[206:209], v145 offset:5120
	ds_read_b128 v[210:213], v145 offset:6144
	ds_read_b128 v[228:231], v145 offset:7168
	global_load_lds_dwordx4 v[140:141], off
	v_lshl_add_u64 v[140:141], s[62:63], 0, v[136:137]
	s_add_i32 m0, s96, 0xe000
	s_nop 0
	global_load_lds_dwordx4 v[140:141], off
	s_waitcnt vmcnt(8)
	s_waitcnt lgkmcnt(0)
	s_barrier
	s_setprio 1
	s_waitcnt lgkmcnt(0)
	v_mfma_f32_16x16x32_bf16 v[126:129], v[146:149], v[178:181], v[126:129]
	v_mfma_f32_16x16x32_bf16 v[122:125], v[154:157], v[178:181], v[122:125]
	v_mfma_f32_16x16x32_bf16 v[118:121], v[146:149], v[186:189], v[118:121]
	v_mfma_f32_16x16x32_bf16 v[110:113], v[154:157], v[186:189], v[110:113]
	v_mfma_f32_16x16x32_bf16 v[102:105], v[146:149], v[202:205], v[102:105]
	v_mfma_f32_16x16x32_bf16 v[94:97], v[154:157], v[202:205], v[94:97]
	v_mfma_f32_16x16x32_bf16 v[86:89], v[146:149], v[210:213], v[86:89]
	v_mfma_f32_16x16x32_bf16 v[78:81], v[154:157], v[210:213], v[78:81]
	v_mfma_f32_16x16x32_bf16 v[126:129], v[150:153], v[182:185], v[126:129]
	v_mfma_f32_16x16x32_bf16 v[122:125], v[158:161], v[182:185], v[122:125]
	v_mfma_f32_16x16x32_bf16 v[118:121], v[150:153], v[190:193], v[118:121]
	v_mfma_f32_16x16x32_bf16 v[110:113], v[158:161], v[190:193], v[110:113]
	v_mfma_f32_16x16x32_bf16 v[102:105], v[150:153], v[206:209], v[102:105]
	v_mfma_f32_16x16x32_bf16 v[94:97], v[158:161], v[206:209], v[94:97]
	v_mfma_f32_16x16x32_bf16 v[86:89], v[150:153], v[228:231], v[86:89]
	v_mfma_f32_16x16x32_bf16 v[78:81], v[158:161], v[228:231], v[78:81]
	v_mfma_f32_16x16x32_bf16 v[114:117], v[162:165], v[178:181], v[114:117]
	v_mfma_f32_16x16x32_bf16 v[106:109], v[170:173], v[178:181], v[106:109]
	v_mfma_f32_16x16x32_bf16 v[98:101], v[162:165], v[186:189], v[98:101]
	v_mfma_f32_16x16x32_bf16 v[90:93], v[170:173], v[186:189], v[90:93]
	v_mfma_f32_16x16x32_bf16 v[82:85], v[162:165], v[202:205], v[82:85]
	v_mfma_f32_16x16x32_bf16 v[74:77], v[170:173], v[202:205], v[74:77]
	v_mfma_f32_16x16x32_bf16 v[70:73], v[162:165], v[210:213], v[70:73]
	v_mfma_f32_16x16x32_bf16 v[66:69], v[170:173], v[210:213], v[66:69]
	v_mfma_f32_16x16x32_bf16 v[114:117], v[166:169], v[182:185], v[114:117]
	v_mfma_f32_16x16x32_bf16 v[106:109], v[174:177], v[182:185], v[106:109]
	v_mfma_f32_16x16x32_bf16 v[98:101], v[166:169], v[190:193], v[98:101]
	v_mfma_f32_16x16x32_bf16 v[90:93], v[174:177], v[190:193], v[90:93]
	v_mfma_f32_16x16x32_bf16 v[82:85], v[166:169], v[206:209], v[82:85]
	v_mfma_f32_16x16x32_bf16 v[74:77], v[174:177], v[206:209], v[74:77]
	v_mfma_f32_16x16x32_bf16 v[70:73], v[166:169], v[228:231], v[70:73]
	v_mfma_f32_16x16x32_bf16 v[66:69], v[174:177], v[228:231], v[66:69]
	s_setprio 0
	s_barrier
	s_add_i32 vcc_hi, vcc_hi, s91
	v_lshl_add_u64 v[140:141], s[30:31], 0, v[0:1]
	s_mov_b32 m0, vcc_hi
	ds_read_b128 v[178:181], v145 offset:16384
	ds_read_b128 v[182:185], v145 offset:17408
	ds_read_b128 v[186:189], v145 offset:18432
	ds_read_b128 v[190:193], v145 offset:19456
	ds_read_b128 v[202:205], v145 offset:20480
	ds_read_b128 v[206:209], v145 offset:21504
	ds_read_b128 v[210:213], v145 offset:22528
	ds_read_b128 v[228:231], v145 offset:23552
	global_load_lds_dwordx4 v[140:141], off
	s_add_i32 m0, vcc_hi, 0x2000
	v_lshl_add_u64 v[194:195], s[30:31], 0, v[134:135]
	s_add_u32 s30, s30, s69
	s_addc_u32 s31, s31, 0
	s_add_i32 s77, s77, s91
	global_load_lds_dwordx4 v[194:195], off
	v_lshl_add_u64 v[196:197], s[30:31], 0, v[0:1]
	s_mov_b32 m0, s77
	v_lshl_add_u64 v[198:199], s[30:31], 0, v[134:135]
	global_load_lds_dwordx4 v[196:197], off
	s_add_i32 m0, s77, 0x2000
	v_lshl_add_u64 v[214:215], s[72:73], 0, v[130:131]
	global_load_lds_dwordx4 v[198:199], off
	s_mov_b32 m0, s96
	v_lshl_add_u64 v[232:233], s[72:73], 0, v[132:133]
	global_load_lds_dwordx4 v[214:215], off
	s_mov_b32 m0, s4
	s_nop 0
	global_load_lds_dwordx4 v[232:233], off
	s_waitcnt vmcnt(8)
	s_waitcnt lgkmcnt(0)
	s_barrier
; #define PG8_STAGE(bufoff, gbase, voff) do { _Pragma("unroll") for (int _i = 0; _i < 2; ++_i) \
;         __builtin_amdgcn_global_load_lds((const unsigned*)((const char*)(gbase) + (voff)[_i]), (LAS unsigned*)(lds + (bufoff) + ldsw + _i * 8192), 16, 0, 0); } while (0)
; #define PG8_LDA(dst, b, h) do { _Pragma("unroll") for (int m = 0; m < 4; ++m) _Pragma("unroll") for (int k = 0; k < 2; ++k) dst[m][k] = *(const LAS bf16x8*)(lds + PG8_SA(b, h) + aoff + m * 2048 + k * 1024); } while (0)
; #define PG8_LDB(dst, b, h) do { _Pragma("unroll") for (int n = 0; n < 2; ++n) _Pragma("unroll") for (int k = 0; k < 2; ++k) dst[n][k] = *(const LAS bf16x8*)(lds + PG8_SB(b, h) + boff + n * 2048 + k * 1024); } while (0)
; #define PG8_MMA(ai, bj, At, Bt) do { __builtin_amdgcn_s_setprio(1); _Pragma("unroll") for (int m = 0; m < 4; ++m) _Pragma("unroll") for (int n = 0; n < 2; ++n) _Pragma("unroll") for (int k = 0; k < 2; ++k) \
;         acc[ai][bj][m][n] = __builtin_amdgcn_mfma_f32_16x16x32_bf16(Bt[n][k], At[m][k], acc[ai][bj][m][n], 0, 0, 0); __builtin_amdgcn_s_setprio(0); } while (0)
; #define PG8_WAIT_V(n) asm volatile("s_waitcnt vmcnt(" #n ")" ::: "memory")
; #define PG8_WAIT_L(n) asm volatile("s_waitcnt lgkmcnt(" #n ")" ::: "memory")
; #define PG8_BAR __builtin_amdgcn_s_barrier()
; #define PG8_SCHED __builtin_amdgcn_sched_barrier(0)
; template <class Epi>
; __device__ __forceinline__ void gemm_phase(LAS unsigned char* lds, const Gemm g, const StaticOrder& S, const Epi& E) {
;     ...
;             PG8_WAIT_V(8); PG8_WAIT_L(0); PG8_BAR; PG8_MMA(1, 0, At, B0); PG8_MMA(1, 1, At, B1); PG8_BAR; PG8_SCHED;
;             PG8_LDB(B0, 1, 0); PG8_LDB(B1, 1, 1); PG8_SCHED; PG8_LDA(At, 1, 0); PG8_STAGE(PG8_SA(0, 1), a2 + hstepA, voffA);
;             PG8_WAIT_V(8); PG8_WAIT_L(0); PG8_BAR; PG8_MMA(0, 0, At, B0); PG8_MMA(0, 1, At, B1); PG8_BAR; PG8_SCHED;
	s_setprio 1
	s_waitcnt lgkmcnt(0)
	v_mfma_f32_16x16x32_bf16 v[62:65], v[146:149], v[178:181], v[62:65]
	v_mfma_f32_16x16x32_bf16 v[58:61], v[154:157], v[178:181], v[58:61]
	v_mfma_f32_16x16x32_bf16 v[54:57], v[146:149], v[186:189], v[54:57]
	v_mfma_f32_16x16x32_bf16 v[46:49], v[154:157], v[186:189], v[46:49]
	v_mfma_f32_16x16x32_bf16 v[38:41], v[146:149], v[202:205], v[38:41]
	v_mfma_f32_16x16x32_bf16 v[30:33], v[154:157], v[202:205], v[30:33]
	v_mfma_f32_16x16x32_bf16 v[22:25], v[146:149], v[210:213], v[22:25]
	v_mfma_f32_16x16x32_bf16 v[14:17], v[154:157], v[210:213], v[14:17]
	v_mfma_f32_16x16x32_bf16 v[62:65], v[150:153], v[182:185], v[62:65]
	v_mfma_f32_16x16x32_bf16 v[58:61], v[158:161], v[182:185], v[58:61]
	v_mfma_f32_16x16x32_bf16 v[54:57], v[150:153], v[190:193], v[54:57]
	v_mfma_f32_16x16x32_bf16 v[46:49], v[158:161], v[190:193], v[46:49]
	v_mfma_f32_16x16x32_bf16 v[38:41], v[150:153], v[206:209], v[38:41]
	v_mfma_f32_16x16x32_bf16 v[30:33], v[158:161], v[206:209], v[30:33]
	v_mfma_f32_16x16x32_bf16 v[22:25], v[150:153], v[228:231], v[22:25]
	v_mfma_f32_16x16x32_bf16 v[14:17], v[158:161], v[228:231], v[14:17]
	v_mfma_f32_16x16x32_bf16 v[50:53], v[162:165], v[178:181], v[50:53]
	v_mfma_f32_16x16x32_bf16 v[42:45], v[170:173], v[178:181], v[42:45]
	v_mfma_f32_16x16x32_bf16 v[34:37], v[162:165], v[186:189], v[34:37]
	v_mfma_f32_16x16x32_bf16 v[26:29], v[170:173], v[186:189], v[26:29]
	v_mfma_f32_16x16x32_bf16 v[18:21], v[162:165], v[202:205], v[18:21]
	v_mfma_f32_16x16x32_bf16 v[10:13], v[170:173], v[202:205], v[10:13]
	v_mfma_f32_16x16x32_bf16 v[6:9], v[162:165], v[210:213], v[6:9]
	v_mfma_f32_16x16x32_bf16 v[2:5], v[170:173], v[210:213], v[2:5]
	v_mfma_f32_16x16x32_bf16 v[50:53], v[166:169], v[182:185], v[50:53]
	v_mfma_f32_16x16x32_bf16 v[42:45], v[174:177], v[182:185], v[42:45]
	v_mfma_f32_16x16x32_bf16 v[34:37], v[166:169], v[190:193], v[34:37]
	v_mfma_f32_16x16x32_bf16 v[26:29], v[174:177], v[190:193], v[26:29]
	v_mfma_f32_16x16x32_bf16 v[18:21], v[166:169], v[206:209], v[18:21]
	v_mfma_f32_16x16x32_bf16 v[10:13], v[174:177], v[206:209], v[10:13]
	v_mfma_f32_16x16x32_bf16 v[6:9], v[166:169], v[228:231], v[6:9]
	v_mfma_f32_16x16x32_bf16 v[2:5], v[174:177], v[228:231], v[2:5]
	s_setprio 0
	s_barrier
	s_add_i32 s77, 0, 0x18000
	s_add_i32 vcc_hi, 0, 0x1c000
	v_add_u32_e32 v158, s77, v143
	v_add_u32_e32 v174, vcc_hi, v143
	ds_read_b128 v[146:149], v158
	ds_read_b128 v[150:153], v158 offset:1024
	ds_read_b128 v[154:157], v158 offset:2048
	ds_read_b128 v[158:161], v158 offset:3072
	ds_read_b128 v[162:165], v174
	ds_read_b128 v[166:169], v174 offset:1024
	ds_read_b128 v[170:173], v174 offset:2048
	ds_read_b128 v[174:177], v174 offset:3072
	s_add_u32 s30, s72, s18
	s_addc_u32 s31, s73, 0
	s_mov_b32 m0, s5
	v_lshl_add_u64 v[234:235], s[30:31], 0, v[130:131]
	ds_read_b128 v[178:181], v145 offset:32768
	ds_read_b128 v[182:185], v145 offset:33792
	ds_read_b128 v[186:189], v145 offset:34816
	ds_read_b128 v[190:193], v145 offset:35840
	ds_read_b128 v[202:205], v145 offset:36864
	ds_read_b128 v[206:209], v145 offset:37888
	ds_read_b128 v[210:213], v145 offset:38912
	ds_read_b128 v[228:231], v145 offset:39936
	global_load_lds_dwordx4 v[234:235], off
	v_lshl_add_u64 v[234:235], s[30:31], 0, v[132:133]
	s_mov_b32 m0, s6
	s_nop 0
	global_load_lds_dwordx4 v[234:235], off
	s_waitcnt vmcnt(8)
	s_waitcnt lgkmcnt(0)
	s_barrier
	s_setprio 1
	s_waitcnt lgkmcnt(0)
	v_mfma_f32_16x16x32_bf16 v[126:129], v[146:149], v[178:181], v[126:129]
	v_mfma_f32_16x16x32_bf16 v[122:125], v[154:157], v[178:181], v[122:125]
	v_mfma_f32_16x16x32_bf16 v[118:121], v[146:149], v[186:189], v[118:121]
	v_mfma_f32_16x16x32_bf16 v[110:113], v[154:157], v[186:189], v[110:113]
	v_mfma_f32_16x16x32_bf16 v[102:105], v[146:149], v[202:205], v[102:105]
	v_mfma_f32_16x16x32_bf16 v[94:97], v[154:157], v[202:205], v[94:97]
	v_mfma_f32_16x16x32_bf16 v[86:89], v[146:149], v[210:213], v[86:89]
	v_mfma_f32_16x16x32_bf16 v[78:81], v[154:157], v[210:213], v[78:81]
	v_mfma_f32_16x16x32_bf16 v[126:129], v[150:153], v[182:185], v[126:129]
	v_mfma_f32_16x16x32_bf16 v[122:125], v[158:161], v[182:185], v[122:125]
	v_mfma_f32_16x16x32_bf16 v[118:121], v[150:153], v[190:193], v[118:121]
	v_mfma_f32_16x16x32_bf16 v[110:113], v[158:161], v[190:193], v[110:113]
	v_mfma_f32_16x16x32_bf16 v[102:105], v[150:153], v[206:209], v[102:105]
	v_mfma_f32_16x16x32_bf16 v[94:97], v[158:161], v[206:209], v[94:97]
	v_mfma_f32_16x16x32_bf16 v[86:89], v[150:153], v[228:231], v[86:89]
	v_mfma_f32_16x16x32_bf16 v[78:81], v[158:161], v[228:231], v[78:81]
	v_mfma_f32_16x16x32_bf16 v[114:117], v[162:165], v[178:181], v[114:117]
	v_mfma_f32_16x16x32_bf16 v[106:109], v[170:173], v[178:181], v[106:109]
	v_mfma_f32_16x16x32_bf16 v[98:101], v[162:165], v[186:189], v[98:101]
	v_mfma_f32_16x16x32_bf16 v[90:93], v[170:173], v[186:189], v[90:93]
	v_mfma_f32_16x16x32_bf16 v[82:85], v[162:165], v[202:205], v[82:85]
	v_mfma_f32_16x16x32_bf16 v[74:77], v[170:173], v[202:205], v[74:77]
	v_mfma_f32_16x16x32_bf16 v[70:73], v[162:165], v[210:213], v[70:73]
	v_mfma_f32_16x16x32_bf16 v[66:69], v[170:173], v[210:213], v[66:69]
	v_mfma_f32_16x16x32_bf16 v[114:117], v[166:169], v[182:185], v[114:117]
	v_mfma_f32_16x16x32_bf16 v[106:109], v[174:177], v[182:185], v[106:109]
	v_mfma_f32_16x16x32_bf16 v[98:101], v[166:169], v[190:193], v[98:101]
	v_mfma_f32_16x16x32_bf16 v[90:93], v[174:177], v[190:193], v[90:93]
	v_mfma_f32_16x16x32_bf16 v[82:85], v[166:169], v[206:209], v[82:85]
	v_mfma_f32_16x16x32_bf16 v[74:77], v[174:177], v[206:209], v[74:77]
	v_mfma_f32_16x16x32_bf16 v[70:73], v[166:169], v[228:231], v[70:73]
	v_mfma_f32_16x16x32_bf16 v[66:69], v[174:177], v[228:231], v[66:69]
	s_setprio 0
	s_barrier
; #define PG8_STAGE(bufoff, gbase, voff) do { _Pragma("unroll") for (int _i = 0; _i < 2; ++_i) \
;         __builtin_amdgcn_global_load_lds((const unsigned*)((const char*)(gbase) + (voff)[_i]), (LAS unsigned*)(lds + (bufoff) + ldsw + _i * 8192), 16, 0, 0); } while (0)
; #define PG8_LDA(dst, b, h) do { _Pragma("unroll") for (int m = 0; m < 4; ++m) _Pragma("unroll") for (int k = 0; k < 2; ++k) dst[m][k] = *(const LAS bf16x8*)(lds + PG8_SA(b, h) + aoff + m * 2048 + k * 1024); } while (0)
; #define PG8_MMA(ai, bj, At, Bt) do { __builtin_amdgcn_s_setprio(1); _Pragma("unroll") for (int m = 0; m < 4; ++m) _Pragma("unroll") for (int n = 0; n < 2; ++n) _Pragma("unroll") for (int k = 0; k < 2; ++k) \
;         acc[ai][bj][m][n] = __builtin_amdgcn_mfma_f32_16x16x32_bf16(Bt[n][k], At[m][k], acc[ai][bj][m][n], 0, 0, 0); __builtin_amdgcn_s_setprio(0); } while (0)
; #define PG8_WAIT_V(n) asm volatile("s_waitcnt vmcnt(" #n ")" ::: "memory")
; #define PG8_WAIT_L(n) asm volatile("s_waitcnt lgkmcnt(" #n ")" ::: "memory")
; #define PG8_BAR __builtin_amdgcn_s_barrier()
; #define PG8_SCHED __builtin_amdgcn_sched_barrier(0)
; template <class Epi>
; __device__ __forceinline__ void gemm_phase(LAS unsigned char* lds, const Gemm g, const StaticOrder& S, const Epi& E) {
;     ...
;             PG8_LDA(At, 1, 1); PG8_STAGE(PG8_SB(1, 0), b3, voffB); PG8_STAGE(PG8_SB(1, 1), b3 + hstepB, voffB); PG8_STAGE(PG8_SA(1, 0), a3, voffA);
;             PG8_WAIT_V(8); PG8_WAIT_L(0); PG8_BAR; PG8_MMA(1, 0, At, B0); PG8_MMA(1, 1, At, B1); PG8_BAR; PG8_SCHED;
;         }
;         if (wr == 0) PG8_BAR;
	s_add_i32 s30, s77, s91
	v_lshl_add_u64 v[140:141], v[140:141], 0, s[24:25]
	s_mov_b32 m0, s30
	ds_read_b128 v[178:181], v145 offset:49152
	ds_read_b128 v[182:185], v145 offset:50176
	ds_read_b128 v[186:189], v145 offset:51200
	ds_read_b128 v[190:193], v145 offset:52224
	ds_read_b128 v[202:205], v145 offset:53248
	ds_read_b128 v[206:209], v145 offset:54272
	ds_read_b128 v[210:213], v145 offset:55296
	ds_read_b128 v[228:231], v145 offset:56320
	global_load_lds_dwordx4 v[140:141], off
	v_lshl_add_u64 v[140:141], v[194:195], 0, s[24:25]
	s_add_i32 m0, s30, 0x2000
	s_add_i32 s30, vcc_hi, s91
	global_load_lds_dwordx4 v[140:141], off
	v_lshl_add_u64 v[140:141], v[196:197], 0, s[24:25]
	s_mov_b32 m0, s30
	s_nop 0
	global_load_lds_dwordx4 v[140:141], off
	v_lshl_add_u64 v[140:141], v[198:199], 0, s[24:25]
	s_add_i32 m0, s30, 0x2000
	s_nop 0
	global_load_lds_dwordx4 v[140:141], off
	v_lshl_add_u64 v[140:141], v[214:215], 0, s[24:25]
	s_mov_b32 m0, s97
	s_nop 0
	global_load_lds_dwordx4 v[140:141], off
	v_lshl_add_u64 v[140:141], v[232:233], 0, s[24:25]
	s_mov_b32 m0, s16
	s_nop 0
	global_load_lds_dwordx4 v[140:141], off
	s_waitcnt vmcnt(8)
	s_waitcnt lgkmcnt(0)
	s_barrier
	s_setprio 1
	s_waitcnt lgkmcnt(0)
	v_mfma_f32_16x16x32_bf16 v[62:65], v[146:149], v[178:181], v[62:65]
	v_mfma_f32_16x16x32_bf16 v[58:61], v[154:157], v[178:181], v[58:61]
	v_mfma_f32_16x16x32_bf16 v[54:57], v[146:149], v[186:189], v[54:57]
	v_mfma_f32_16x16x32_bf16 v[46:49], v[154:157], v[186:189], v[46:49]
	v_mfma_f32_16x16x32_bf16 v[38:41], v[146:149], v[202:205], v[38:41]
	v_mfma_f32_16x16x32_bf16 v[30:33], v[154:157], v[202:205], v[30:33]
	v_mfma_f32_16x16x32_bf16 v[22:25], v[146:149], v[210:213], v[22:25]
	v_mfma_f32_16x16x32_bf16 v[14:17], v[154:157], v[210:213], v[14:17]
	v_mfma_f32_16x16x32_bf16 v[62:65], v[150:153], v[182:185], v[62:65]
	v_mfma_f32_16x16x32_bf16 v[58:61], v[158:161], v[182:185], v[58:61]
	v_mfma_f32_16x16x32_bf16 v[54:57], v[150:153], v[190:193], v[54:57]
	v_mfma_f32_16x16x32_bf16 v[46:49], v[158:161], v[190:193], v[46:49]
	v_mfma_f32_16x16x32_bf16 v[38:41], v[150:153], v[206:209], v[38:41]
	v_mfma_f32_16x16x32_bf16 v[30:33], v[158:161], v[206:209], v[30:33]
	v_mfma_f32_16x16x32_bf16 v[22:25], v[150:153], v[228:231], v[22:25]
	v_mfma_f32_16x16x32_bf16 v[14:17], v[158:161], v[228:231], v[14:17]
	v_mfma_f32_16x16x32_bf16 v[50:53], v[162:165], v[178:181], v[50:53]
	v_mfma_f32_16x16x32_bf16 v[42:45], v[170:173], v[178:181], v[42:45]
	v_mfma_f32_16x16x32_bf16 v[34:37], v[162:165], v[186:189], v[34:37]
	v_mfma_f32_16x16x32_bf16 v[26:29], v[170:173], v[186:189], v[26:29]
	v_mfma_f32_16x16x32_bf16 v[18:21], v[162:165], v[202:205], v[18:21]
	v_mfma_f32_16x16x32_bf16 v[10:13], v[170:173], v[202:205], v[10:13]
	v_mfma_f32_16x16x32_bf16 v[6:9], v[162:165], v[210:213], v[6:9]
	v_mfma_f32_16x16x32_bf16 v[2:5], v[170:173], v[210:213], v[2:5]
	v_mfma_f32_16x16x32_bf16 v[50:53], v[166:169], v[182:185], v[50:53]
	v_mfma_f32_16x16x32_bf16 v[42:45], v[174:177], v[182:185], v[42:45]
	v_mfma_f32_16x16x32_bf16 v[34:37], v[166:169], v[190:193], v[34:37]
	v_mfma_f32_16x16x32_bf16 v[26:29], v[174:177], v[190:193], v[26:29]
	v_mfma_f32_16x16x32_bf16 v[18:21], v[166:169], v[206:209], v[18:21]
	v_mfma_f32_16x16x32_bf16 v[10:13], v[174:177], v[206:209], v[10:13]
	v_mfma_f32_16x16x32_bf16 v[6:9], v[166:169], v[228:231], v[6:9]
	v_mfma_f32_16x16x32_bf16 v[2:5], v[174:177], v[228:231], v[2:5]
	s_setprio 0
	s_barrier
	s_add_u32 s14, s14, 0x100
	s_addc_u32 s15, s15, 0
	s_add_u32 s62, s62, 0x100
	s_addc_u32 s63, s63, 0
	s_cmp_ge_u32 vcc_lo, s11
	s_mov_b32 s72, vcc_lo
	s_cbranch_scc0 .LBB0_292
	s_and_b64 vcc, exec, s[52:53]
	s_cbranch_vccz .LBB0_295
	s_barrier
